# GEMM K-loops: the first K iteration after a unit epilogue no longer waits on vmcnt in its first two load segments (its tiles were retired by the epilogue wait), so epilogue stores drain under MFMAs
# baseline (speedup 1.0000x reference)
_Z6mk_fwd4Args:
	s_load_dword s33, s[0:1], 0xc0
	s_add_u32 s4, s0, 0xc0
	s_addc_u32 s5, s1, 0
	v_readfirstlane_b32 s10, v0
	s_mov_b32 s100, 0
	v_writelane_b32 v252, s4, 0
	s_nop 1
	v_writelane_b32 v252, s5, 1
	s_waitcnt lgkmcnt(0)
	s_and_b32 s4, s33, 7
	s_cmp_lg_u32 s4, 0
	v_writelane_b32 v252, s2, 2
	s_cbranch_scc1 .LBB0_2
	s_ashr_i32 s5, s2, 31
	s_lshr_b32 s5, s5, 29
	s_add_i32 s5, s2, s5
	s_and_b32 s6, s5, -8
	s_ashr_i32 s4, s33, 3
	s_sub_i32 s6, s2, s6
	s_mul_i32 s4, s4, s6
	s_ashr_i32 s5, s5, 3
	s_add_i32 s4, s4, s5
	v_writelane_b32 v252, s4, 2

.LBB0_204:
	s_or_b64 exec, exec, s[4:5]
	s_waitcnt lgkmcnt(0)
	s_barrier
	s_mov_b32 s100, 0

.LBB0_299:
	s_or_b64 exec, exec, s[0:1]
	s_waitcnt lgkmcnt(0)
	s_barrier
	s_mov_b32 s100, 0

.LBB0_322:
	s_add_u32 s4, s0, 0xfffc0080
	s_addc_u32 s5, s1, -1
	s_add_i32 s44, 0, 0x10000
	s_cmp_eq_u32 s93, 12
	s_cselect_b32 s71, s31, s5
	s_cselect_b32 s70, s39, s4
	s_cselect_b32 s69, s41, s92
	s_cselect_b32 s68, s40, s91
	s_add_i32 s4, 0, 0x14000
	v_add_u32_e32 v144, s44, v175
	v_add_u32_e32 v168, s4, v175
	ds_read_b128 v[132:135], v144
	ds_read_b128 v[136:139], v144 offset:1024
	ds_read_b128 v[140:143], v144 offset:2048
	ds_read_b128 v[144:147], v144 offset:3072
	ds_read_b128 v[156:159], v168
	ds_read_b128 v[160:163], v168 offset:1024
	ds_read_b128 v[164:167], v168 offset:2048
	ds_read_b128 v[180:183], v168 offset:3072
	s_add_i32 s94, s77, 0
	v_lshl_add_u64 v[168:169], s[0:1], 0, v[98:99]
	s_add_i32 m0, s94, 0xc000
	ds_read_b128 v[184:187], v179
	ds_read_b128 v[188:191], v179 offset:1024
	ds_read_b128 v[192:195], v179 offset:2048
	ds_read_b128 v[204:207], v179 offset:3072
	ds_read_b128 v[208:211], v179 offset:4096
	ds_read_b128 v[212:215], v179 offset:5120
	ds_read_b128 v[216:219], v179 offset:6144
	ds_read_b128 v[220:223], v179 offset:7168
	global_load_lds_dwordx4 v[168:169], off
	v_lshl_add_u64 v[168:169], s[0:1], 0, v[150:151]
	s_add_i32 m0, s94, 0xe000
	s_nop 0
	global_load_lds_dwordx4 v[168:169], off
	s_cmp_eq_u32 s100, 1
	s_cbranch_scc1 .Lmy_sk1
	s_waitcnt vmcnt(8)
.Lmy_sk1:
	s_waitcnt lgkmcnt(0)
	s_barrier
	s_setprio 1
	s_waitcnt lgkmcnt(0)
	v_mfma_f32_16x16x32_bf16 v[128:131], v[132:135], v[184:187], v[128:131]
	v_mfma_f32_16x16x32_bf16 v[124:127], v[140:143], v[184:187], v[124:127]
	v_mfma_f32_16x16x32_bf16 v[120:123], v[132:135], v[192:195], v[120:123]
	v_mfma_f32_16x16x32_bf16 v[112:115], v[140:143], v[192:195], v[112:115]
	v_mfma_f32_16x16x32_bf16 v[104:107], v[132:135], v[208:211], v[104:107]
	v_mfma_f32_16x16x32_bf16 v[94:97], v[140:143], v[208:211], v[94:97]
	v_mfma_f32_16x16x32_bf16 v[86:89], v[132:135], v[216:219], v[86:89]
	v_mfma_f32_16x16x32_bf16 v[78:81], v[140:143], v[216:219], v[78:81]
	v_mfma_f32_16x16x32_bf16 v[128:131], v[136:139], v[188:191], v[128:131]
	v_mfma_f32_16x16x32_bf16 v[124:127], v[144:147], v[188:191], v[124:127]
	v_mfma_f32_16x16x32_bf16 v[120:123], v[136:139], v[204:207], v[120:123]
	v_mfma_f32_16x16x32_bf16 v[112:115], v[144:147], v[204:207], v[112:115]
	v_mfma_f32_16x16x32_bf16 v[104:107], v[136:139], v[212:215], v[104:107]
	v_mfma_f32_16x16x32_bf16 v[94:97], v[144:147], v[212:215], v[94:97]
	v_mfma_f32_16x16x32_bf16 v[86:89], v[136:139], v[220:223], v[86:89]
	v_mfma_f32_16x16x32_bf16 v[78:81], v[144:147], v[220:223], v[78:81]
	s_setprio 0
	s_setprio 1
	v_mfma_f32_16x16x32_bf16 v[116:119], v[156:159], v[184:187], v[116:119]
	v_mfma_f32_16x16x32_bf16 v[108:111], v[164:167], v[184:187], v[108:111]
	v_mfma_f32_16x16x32_bf16 v[100:103], v[156:159], v[192:195], v[100:103]
	v_mfma_f32_16x16x32_bf16 v[90:93], v[164:167], v[192:195], v[90:93]
	v_mfma_f32_16x16x32_bf16 v[82:85], v[156:159], v[208:211], v[82:85]
	v_mfma_f32_16x16x32_bf16 v[74:77], v[164:167], v[208:211], v[74:77]
	v_mfma_f32_16x16x32_bf16 v[70:73], v[156:159], v[216:219], v[70:73]
	v_mfma_f32_16x16x32_bf16 v[66:69], v[164:167], v[216:219], v[66:69]
	v_mfma_f32_16x16x32_bf16 v[116:119], v[160:163], v[188:191], v[116:119]
	v_mfma_f32_16x16x32_bf16 v[108:111], v[180:183], v[188:191], v[108:111]
	v_mfma_f32_16x16x32_bf16 v[100:103], v[160:163], v[204:207], v[100:103]
	v_mfma_f32_16x16x32_bf16 v[90:93], v[180:183], v[204:207], v[90:93]
	v_mfma_f32_16x16x32_bf16 v[82:85], v[160:163], v[212:215], v[82:85]
	v_mfma_f32_16x16x32_bf16 v[74:77], v[180:183], v[212:215], v[74:77]
	v_mfma_f32_16x16x32_bf16 v[70:73], v[160:163], v[220:223], v[70:73]
	v_mfma_f32_16x16x32_bf16 v[66:69], v[180:183], v[220:223], v[66:69]
	s_setprio 0
	s_barrier
	s_add_i32 s5, s44, s77
	v_lshl_add_u64 v[168:169], s[68:69], 0, v[148:149]
	s_mov_b32 m0, s5
	ds_read_b128 v[184:187], v179 offset:16384
	ds_read_b128 v[188:191], v179 offset:17408
	ds_read_b128 v[192:195], v179 offset:18432
	ds_read_b128 v[204:207], v179 offset:19456
	ds_read_b128 v[208:211], v179 offset:20480
	ds_read_b128 v[212:215], v179 offset:21504
	ds_read_b128 v[216:219], v179 offset:22528
	ds_read_b128 v[220:223], v179 offset:23552
	global_load_lds_dwordx4 v[168:169], off
	s_add_i32 m0, s5, 0x2000
	s_add_u32 s44, s68, 0x40000
	v_lshl_add_u64 v[172:173], s[68:69], 0, v[152:153]
	s_addc_u32 s45, s69, 0
	s_add_i32 s4, s4, s77
	global_load_lds_dwordx4 v[172:173], off
	v_lshl_add_u64 v[176:177], s[44:45], 0, v[148:149]
	s_mov_b32 m0, s4
	v_lshl_add_u64 v[200:201], s[70:71], 0, v[150:151]
	global_load_lds_dwordx4 v[176:177], off
	v_lshl_add_u64 v[176:177], s[44:45], 0, v[152:153]
	s_add_i32 m0, s4, 0x2000
	s_nop 0
	global_load_lds_dwordx4 v[176:177], off
	v_lshl_add_u64 v[176:177], s[70:71], 0, v[98:99]
	s_mov_b32 m0, s94
	s_nop 0
	global_load_lds_dwordx4 v[176:177], off
	s_add_i32 m0, s94, 0x2000
	s_nop 0
	global_load_lds_dwordx4 v[200:201], off
	s_cmp_eq_u32 s100, 1
	s_cbranch_scc1 .Lmy_sk2
	s_waitcnt vmcnt(8)
.Lmy_sk2:
	s_waitcnt lgkmcnt(0)
	s_barrier
	s_setprio 1
	s_waitcnt lgkmcnt(0)
	v_mfma_f32_16x16x32_bf16 v[62:65], v[132:135], v[184:187], v[62:65]
	v_mfma_f32_16x16x32_bf16 v[58:61], v[140:143], v[184:187], v[58:61]
	v_mfma_f32_16x16x32_bf16 v[54:57], v[132:135], v[192:195], v[54:57]
	v_mfma_f32_16x16x32_bf16 v[46:49], v[140:143], v[192:195], v[46:49]
	v_mfma_f32_16x16x32_bf16 v[38:41], v[132:135], v[208:211], v[38:41]
	v_mfma_f32_16x16x32_bf16 v[30:33], v[140:143], v[208:211], v[30:33]
	v_mfma_f32_16x16x32_bf16 v[22:25], v[132:135], v[216:219], v[22:25]
	v_mfma_f32_16x16x32_bf16 v[14:17], v[140:143], v[216:219], v[14:17]
	v_mfma_f32_16x16x32_bf16 v[62:65], v[136:139], v[188:191], v[62:65]
	v_mfma_f32_16x16x32_bf16 v[58:61], v[144:147], v[188:191], v[58:61]
	v_mfma_f32_16x16x32_bf16 v[54:57], v[136:139], v[204:207], v[54:57]
	v_mfma_f32_16x16x32_bf16 v[46:49], v[144:147], v[204:207], v[46:49]
	v_mfma_f32_16x16x32_bf16 v[38:41], v[136:139], v[212:215], v[38:41]
	v_mfma_f32_16x16x32_bf16 v[30:33], v[144:147], v[212:215], v[30:33]
	v_mfma_f32_16x16x32_bf16 v[22:25], v[136:139], v[220:223], v[22:25]
	v_mfma_f32_16x16x32_bf16 v[14:17], v[144:147], v[220:223], v[14:17]
	s_setprio 0
	s_setprio 1
	v_mfma_f32_16x16x32_bf16 v[50:53], v[156:159], v[184:187], v[50:53]
	v_mfma_f32_16x16x32_bf16 v[42:45], v[164:167], v[184:187], v[42:45]
	v_mfma_f32_16x16x32_bf16 v[34:37], v[156:159], v[192:195], v[34:37]
	v_mfma_f32_16x16x32_bf16 v[26:29], v[164:167], v[192:195], v[26:29]
	v_mfma_f32_16x16x32_bf16 v[18:21], v[156:159], v[208:211], v[18:21]
	v_mfma_f32_16x16x32_bf16 v[10:13], v[164:167], v[208:211], v[10:13]
	v_mfma_f32_16x16x32_bf16 v[6:9], v[156:159], v[216:219], v[6:9]
	v_mfma_f32_16x16x32_bf16 v[2:5], v[164:167], v[216:219], v[2:5]
	v_mfma_f32_16x16x32_bf16 v[50:53], v[160:163], v[188:191], v[50:53]
	v_mfma_f32_16x16x32_bf16 v[42:45], v[180:183], v[188:191], v[42:45]
	v_mfma_f32_16x16x32_bf16 v[34:37], v[160:163], v[204:207], v[34:37]
	v_mfma_f32_16x16x32_bf16 v[26:29], v[180:183], v[204:207], v[26:29]
	v_mfma_f32_16x16x32_bf16 v[18:21], v[160:163], v[212:215], v[18:21]
	v_mfma_f32_16x16x32_bf16 v[10:13], v[180:183], v[212:215], v[10:13]
	v_mfma_f32_16x16x32_bf16 v[6:9], v[160:163], v[220:223], v[6:9]
	v_mfma_f32_16x16x32_bf16 v[2:5], v[180:183], v[220:223], v[2:5]
	s_setprio 0
	s_barrier
	s_add_i32 s4, 0, 0x18000
	s_add_i32 s5, 0, 0x1c000
	v_add_u32_e32 v144, s4, v175
	v_add_u32_e32 v170, s5, v175
	ds_read_b128 v[132:135], v144
	ds_read_b128 v[136:139], v144 offset:1024
	ds_read_b128 v[140:143], v144 offset:2048
	ds_read_b128 v[144:147], v144 offset:3072
	ds_read_b128 v[156:159], v170
	ds_read_b128 v[160:163], v170 offset:1024
	ds_read_b128 v[164:167], v170 offset:2048
	ds_read_b128 v[180:183], v170 offset:3072
	s_add_u32 s44, s70, 0x40000
	s_addc_u32 s45, s71, 0
	v_lshl_add_u64 v[202:203], s[44:45], 0, v[98:99]
	s_add_i32 m0, s94, 0x4000
	ds_read_b128 v[184:187], v179 offset:32768
	ds_read_b128 v[188:191], v179 offset:33792
	ds_read_b128 v[192:195], v179 offset:34816
	ds_read_b128 v[204:207], v179 offset:35840
	ds_read_b128 v[208:211], v179 offset:36864
	ds_read_b128 v[212:215], v179 offset:37888
	ds_read_b128 v[216:219], v179 offset:38912
	ds_read_b128 v[220:223], v179 offset:39936
	global_load_lds_dwordx4 v[202:203], off
	v_lshl_add_u64 v[202:203], s[44:45], 0, v[150:151]
	s_add_i32 m0, s94, 0x6000
	s_nop 0
	global_load_lds_dwordx4 v[202:203], off
	s_waitcnt vmcnt(8)
	s_waitcnt lgkmcnt(0)
	s_barrier
	s_setprio 1
	s_waitcnt lgkmcnt(0)
	v_mfma_f32_16x16x32_bf16 v[128:131], v[132:135], v[184:187], v[128:131]
	v_mfma_f32_16x16x32_bf16 v[124:127], v[140:143], v[184:187], v[124:127]
	v_mfma_f32_16x16x32_bf16 v[120:123], v[132:135], v[192:195], v[120:123]
	v_mfma_f32_16x16x32_bf16 v[112:115], v[140:143], v[192:195], v[112:115]
	v_mfma_f32_16x16x32_bf16 v[104:107], v[132:135], v[208:211], v[104:107]
	v_mfma_f32_16x16x32_bf16 v[94:97], v[140:143], v[208:211], v[94:97]
	v_mfma_f32_16x16x32_bf16 v[86:89], v[132:135], v[216:219], v[86:89]
	v_mfma_f32_16x16x32_bf16 v[78:81], v[140:143], v[216:219], v[78:81]
	v_mfma_f32_16x16x32_bf16 v[128:131], v[136:139], v[188:191], v[128:131]
	v_mfma_f32_16x16x32_bf16 v[124:127], v[144:147], v[188:191], v[124:127]
	v_mfma_f32_16x16x32_bf16 v[120:123], v[136:139], v[204:207], v[120:123]
	v_mfma_f32_16x16x32_bf16 v[112:115], v[144:147], v[204:207], v[112:115]
	v_mfma_f32_16x16x32_bf16 v[104:107], v[136:139], v[212:215], v[104:107]
	v_mfma_f32_16x16x32_bf16 v[94:97], v[144:147], v[212:215], v[94:97]
	v_mfma_f32_16x16x32_bf16 v[86:89], v[136:139], v[220:223], v[86:89]
	v_mfma_f32_16x16x32_bf16 v[78:81], v[144:147], v[220:223], v[78:81]
	s_setprio 0
	s_setprio 1
	v_mfma_f32_16x16x32_bf16 v[116:119], v[156:159], v[184:187], v[116:119]
	v_mfma_f32_16x16x32_bf16 v[108:111], v[164:167], v[184:187], v[108:111]
	v_mfma_f32_16x16x32_bf16 v[100:103], v[156:159], v[192:195], v[100:103]
	v_mfma_f32_16x16x32_bf16 v[90:93], v[164:167], v[192:195], v[90:93]
	v_mfma_f32_16x16x32_bf16 v[82:85], v[156:159], v[208:211], v[82:85]
	v_mfma_f32_16x16x32_bf16 v[74:77], v[164:167], v[208:211], v[74:77]
	v_mfma_f32_16x16x32_bf16 v[70:73], v[156:159], v[216:219], v[70:73]
	v_mfma_f32_16x16x32_bf16 v[66:69], v[164:167], v[216:219], v[66:69]
	v_mfma_f32_16x16x32_bf16 v[116:119], v[160:163], v[188:191], v[116:119]
	v_mfma_f32_16x16x32_bf16 v[108:111], v[180:183], v[188:191], v[108:111]
	v_mfma_f32_16x16x32_bf16 v[100:103], v[160:163], v[204:207], v[100:103]
	v_mfma_f32_16x16x32_bf16 v[90:93], v[180:183], v[204:207], v[90:93]
	v_mfma_f32_16x16x32_bf16 v[82:85], v[160:163], v[212:215], v[82:85]
	v_mfma_f32_16x16x32_bf16 v[74:77], v[180:183], v[212:215], v[74:77]
	v_mfma_f32_16x16x32_bf16 v[70:73], v[160:163], v[220:223], v[70:73]
	v_mfma_f32_16x16x32_bf16 v[66:69], v[180:183], v[220:223], v[66:69]
	s_setprio 0
	s_barrier
	s_add_i32 s4, s4, s77
	v_lshl_add_u64 v[168:169], v[168:169], 0, s[42:43]
	s_mov_b32 m0, s4
	ds_read_b128 v[184:187], v179 offset:49152
	ds_read_b128 v[188:191], v179 offset:50176
	ds_read_b128 v[192:195], v179 offset:51200
	ds_read_b128 v[204:207], v179 offset:52224
	ds_read_b128 v[208:211], v179 offset:53248
	ds_read_b128 v[212:215], v179 offset:54272
	ds_read_b128 v[216:219], v179 offset:55296
	ds_read_b128 v[220:223], v179 offset:56320
	global_load_lds_dwordx4 v[168:169], off
	s_add_i32 m0, s4, 0x2000
	s_add_u32 s44, s68, 0x40080
	v_lshl_add_u64 v[168:169], v[172:173], 0, s[42:43]
	s_addc_u32 s45, s69, 0
	s_add_i32 s4, s5, s77
	global_load_lds_dwordx4 v[168:169], off
	v_lshl_add_u64 v[168:169], s[44:45], 0, v[148:149]
	s_mov_b32 m0, s4
	s_nop 0
	global_load_lds_dwordx4 v[168:169], off
	v_lshl_add_u64 v[168:169], s[44:45], 0, v[152:153]
	s_add_i32 m0, s4, 0x2000
	s_nop 0
	global_load_lds_dwordx4 v[168:169], off
	v_lshl_add_u64 v[168:169], v[176:177], 0, s[42:43]
	s_add_i32 m0, s94, 0x8000
	s_nop 0
	global_load_lds_dwordx4 v[168:169], off
	v_lshl_add_u64 v[168:169], v[200:201], 0, s[42:43]
	s_add_i32 m0, s94, 0xa000
	s_nop 0
	global_load_lds_dwordx4 v[168:169], off
	s_waitcnt vmcnt(8)
	s_waitcnt lgkmcnt(0)
	s_barrier
	s_setprio 1
	s_waitcnt lgkmcnt(0)
	v_mfma_f32_16x16x32_bf16 v[62:65], v[132:135], v[184:187], v[62:65]
	v_mfma_f32_16x16x32_bf16 v[58:61], v[140:143], v[184:187], v[58:61]
	v_mfma_f32_16x16x32_bf16 v[54:57], v[132:135], v[192:195], v[54:57]
	v_mfma_f32_16x16x32_bf16 v[46:49], v[140:143], v[192:195], v[46:49]
	v_mfma_f32_16x16x32_bf16 v[38:41], v[132:135], v[208:211], v[38:41]
	v_mfma_f32_16x16x32_bf16 v[30:33], v[140:143], v[208:211], v[30:33]
	v_mfma_f32_16x16x32_bf16 v[22:25], v[132:135], v[216:219], v[22:25]
	v_mfma_f32_16x16x32_bf16 v[14:17], v[140:143], v[216:219], v[14:17]
	v_mfma_f32_16x16x32_bf16 v[62:65], v[136:139], v[188:191], v[62:65]
	v_mfma_f32_16x16x32_bf16 v[58:61], v[144:147], v[188:191], v[58:61]
	v_mfma_f32_16x16x32_bf16 v[54:57], v[136:139], v[204:207], v[54:57]
	v_mfma_f32_16x16x32_bf16 v[46:49], v[144:147], v[204:207], v[46:49]
	v_mfma_f32_16x16x32_bf16 v[38:41], v[136:139], v[212:215], v[38:41]
	v_mfma_f32_16x16x32_bf16 v[30:33], v[144:147], v[212:215], v[30:33]
	v_mfma_f32_16x16x32_bf16 v[22:25], v[136:139], v[220:223], v[22:25]
	v_mfma_f32_16x16x32_bf16 v[14:17], v[144:147], v[220:223], v[14:17]
	s_setprio 0
	s_setprio 1
	v_mfma_f32_16x16x32_bf16 v[50:53], v[156:159], v[184:187], v[50:53]
	v_mfma_f32_16x16x32_bf16 v[42:45], v[164:167], v[184:187], v[42:45]
	v_mfma_f32_16x16x32_bf16 v[34:37], v[156:159], v[192:195], v[34:37]
	v_mfma_f32_16x16x32_bf16 v[26:29], v[164:167], v[192:195], v[26:29]
	v_mfma_f32_16x16x32_bf16 v[18:21], v[156:159], v[208:211], v[18:21]
	v_mfma_f32_16x16x32_bf16 v[10:13], v[164:167], v[208:211], v[10:13]
	v_mfma_f32_16x16x32_bf16 v[6:9], v[156:159], v[216:219], v[6:9]
	v_mfma_f32_16x16x32_bf16 v[2:5], v[164:167], v[216:219], v[2:5]
	v_mfma_f32_16x16x32_bf16 v[50:53], v[160:163], v[188:191], v[50:53]
	v_mfma_f32_16x16x32_bf16 v[42:45], v[180:183], v[188:191], v[42:45]
	v_mfma_f32_16x16x32_bf16 v[34:37], v[160:163], v[204:207], v[34:37]
	v_mfma_f32_16x16x32_bf16 v[26:29], v[180:183], v[204:207], v[26:29]
	v_mfma_f32_16x16x32_bf16 v[18:21], v[160:163], v[212:215], v[18:21]
	v_mfma_f32_16x16x32_bf16 v[10:13], v[180:183], v[212:215], v[10:13]
	v_mfma_f32_16x16x32_bf16 v[6:9], v[160:163], v[220:223], v[6:9]
	v_mfma_f32_16x16x32_bf16 v[2:5], v[180:183], v[220:223], v[2:5]
	s_setprio 0
	s_barrier
	s_mov_b32 s100, 0
	s_add_i32 s93, s93, 2
	s_add_u32 s0, s0, 0x100
	s_addc_u32 s1, s1, 0
	s_add_u32 s91, s91, 0x100
	s_addc_u32 s92, s92, 0
	s_cmp_gt_u32 s93, 13
	s_cbranch_scc0 .LBB0_322
	s_mov_b32 s100, 1
	s_and_b64 vcc, exec, s[14:15]
	s_cbranch_vccz .LBB0_325
	s_barrier

.LBB0_840:
	s_or_b64 exec, exec, s[0:1]
	s_waitcnt vmcnt(0) lgkmcnt(0)
	s_barrier
	s_mov_b32 s100, 0

.LBB0_864:
	s_add_u32 s4, s68, 0xfffc0080
	s_addc_u32 s5, s69, -1
	s_add_i32 s45, 0, 0x10000
	s_cmp_eq_u32 s97, 12
	s_cselect_b32 s75, s57, s5
	s_cselect_b32 s74, s95, s4
	s_cselect_b32 s71, s31, s96
	s_cselect_b32 s70, vcc_lo, vcc_hi
	s_add_i32 s6, 0, 0x14000
	v_add_u32_e32 v104, s45, v239
	v_add_u32_e32 v128, s6, v239
	ds_read_b128 v[90:93], v104
	ds_read_b128 v[94:97], v104 offset:1024
	ds_read_b128 v[100:103], v104 offset:2048
	ds_read_b128 v[104:107], v104 offset:3072
	ds_read_b128 v[108:111], v128
	ds_read_b128 v[112:115], v128 offset:1024
	ds_read_b128 v[120:123], v128 offset:2048
	ds_read_b128 v[128:131], v128 offset:3072
	s_add_i32 s44, s91, 0
	v_lshl_add_u64 v[200:201], s[68:69], 0, v[98:99]
	s_add_i32 m0, s44, 0xc000
	ds_read_b128 v[164:167], v241
	ds_read_b128 v[168:171], v241 offset:1024
	ds_read_b128 v[172:175], v241 offset:2048
	ds_read_b128 v[176:179], v241 offset:3072
	ds_read_b128 v[180:183], v241 offset:4096
	ds_read_b128 v[184:187], v241 offset:5120
	ds_read_b128 v[188:191], v241 offset:6144
	ds_read_b128 v[192:195], v241 offset:7168
	global_load_lds_dwordx4 v[200:201], off
	v_lshl_add_u64 v[200:201], s[68:69], 0, v[206:207]
	s_add_i32 m0, s44, 0xe000
	s_nop 0
	global_load_lds_dwordx4 v[200:201], off
	s_cmp_eq_u32 s100, 1
	s_cbranch_scc1 .Lmy_sk3
	s_waitcnt vmcnt(8)
.Lmy_sk3:
	s_waitcnt lgkmcnt(0)
	s_barrier
	s_setprio 1
	s_waitcnt lgkmcnt(0)
	v_mfma_f32_16x16x32_bf16 v[160:163], v[90:93], v[164:167], v[160:163]
	v_mfma_f32_16x16x32_bf16 v[156:159], v[100:103], v[164:167], v[156:159]
	v_mfma_f32_16x16x32_bf16 v[144:147], v[90:93], v[172:175], v[144:147]
	v_mfma_f32_16x16x32_bf16 v[140:143], v[100:103], v[172:175], v[140:143]
	v_mfma_f32_16x16x32_bf16 v[124:127], v[90:93], v[180:183], v[124:127]
	v_mfma_f32_16x16x32_bf16 v[116:119], v[100:103], v[180:183], v[116:119]
	v_mfma_f32_16x16x32_bf16 v[78:81], v[90:93], v[188:191], v[78:81]
	v_mfma_f32_16x16x32_bf16 v[74:77], v[100:103], v[188:191], v[74:77]
	v_mfma_f32_16x16x32_bf16 v[160:163], v[94:97], v[168:171], v[160:163]
	v_mfma_f32_16x16x32_bf16 v[156:159], v[104:107], v[168:171], v[156:159]
	v_mfma_f32_16x16x32_bf16 v[144:147], v[94:97], v[176:179], v[144:147]
	v_mfma_f32_16x16x32_bf16 v[140:143], v[104:107], v[176:179], v[140:143]
	v_mfma_f32_16x16x32_bf16 v[124:127], v[94:97], v[184:187], v[124:127]
	v_mfma_f32_16x16x32_bf16 v[116:119], v[104:107], v[184:187], v[116:119]
	v_mfma_f32_16x16x32_bf16 v[78:81], v[94:97], v[192:195], v[78:81]
	v_mfma_f32_16x16x32_bf16 v[74:77], v[104:107], v[192:195], v[74:77]
	s_setprio 0
	s_setprio 1
	v_mfma_f32_16x16x32_bf16 v[152:155], v[108:111], v[164:167], v[152:155]
	v_mfma_f32_16x16x32_bf16 v[148:151], v[120:123], v[164:167], v[148:151]
	v_mfma_f32_16x16x32_bf16 v[136:139], v[108:111], v[172:175], v[136:139]
	v_mfma_f32_16x16x32_bf16 v[132:135], v[120:123], v[172:175], v[132:135]
	v_mfma_f32_16x16x32_bf16 v[86:89], v[108:111], v[180:183], v[86:89]
	v_mfma_f32_16x16x32_bf16 v[82:85], v[120:123], v[180:183], v[82:85]
	v_mfma_f32_16x16x32_bf16 v[70:73], v[108:111], v[188:191], v[70:73]
	v_mfma_f32_16x16x32_bf16 v[66:69], v[120:123], v[188:191], v[66:69]
	v_mfma_f32_16x16x32_bf16 v[152:155], v[112:115], v[168:171], v[152:155]
	v_mfma_f32_16x16x32_bf16 v[148:151], v[128:131], v[168:171], v[148:151]
	v_mfma_f32_16x16x32_bf16 v[136:139], v[112:115], v[176:179], v[136:139]
	v_mfma_f32_16x16x32_bf16 v[132:135], v[128:131], v[176:179], v[132:135]
	v_mfma_f32_16x16x32_bf16 v[86:89], v[112:115], v[184:187], v[86:89]
	v_mfma_f32_16x16x32_bf16 v[82:85], v[128:131], v[184:187], v[82:85]
	v_mfma_f32_16x16x32_bf16 v[70:73], v[112:115], v[192:195], v[70:73]
	v_mfma_f32_16x16x32_bf16 v[66:69], v[128:131], v[192:195], v[66:69]
	s_setprio 0
	s_barrier
	s_add_i32 s4, s45, s91
	v_lshl_add_u64 v[200:201], s[70:71], 0, v[204:205]
	s_mov_b32 m0, s4
	ds_read_b128 v[164:167], v241 offset:16384
	ds_read_b128 v[168:171], v241 offset:17408
	ds_read_b128 v[172:175], v241 offset:18432
	ds_read_b128 v[176:179], v241 offset:19456
	ds_read_b128 v[180:183], v241 offset:20480
	ds_read_b128 v[184:187], v241 offset:21504
	ds_read_b128 v[188:191], v241 offset:22528
	ds_read_b128 v[192:195], v241 offset:23552
	global_load_lds_dwordx4 v[200:201], off
	s_add_i32 m0, s4, 0x2000
	s_add_u32 s4, s70, 0x40000
	v_lshl_add_u64 v[202:203], s[70:71], 0, v[208:209]
	s_addc_u32 s5, s71, 0
	s_add_i32 s6, s6, s91
	global_load_lds_dwordx4 v[202:203], off
	v_lshl_add_u64 v[210:211], s[4:5], 0, v[204:205]
	s_mov_b32 m0, s6
	v_lshl_add_u64 v[212:213], s[74:75], 0, v[206:207]
	global_load_lds_dwordx4 v[210:211], off
	v_lshl_add_u64 v[210:211], s[4:5], 0, v[208:209]
	s_add_i32 m0, s6, 0x2000
	s_nop 0
	global_load_lds_dwordx4 v[210:211], off
	v_lshl_add_u64 v[210:211], s[74:75], 0, v[98:99]
	s_mov_b32 m0, s44
	s_nop 0
	global_load_lds_dwordx4 v[210:211], off
	s_add_i32 m0, s44, 0x2000
	s_nop 0
	global_load_lds_dwordx4 v[212:213], off
	s_cmp_eq_u32 s100, 1
	s_cbranch_scc1 .Lmy_sk4
	s_waitcnt vmcnt(8)
.Lmy_sk4:
	s_waitcnt lgkmcnt(0)
	s_barrier
	s_setprio 1
	s_waitcnt lgkmcnt(0)
	v_mfma_f32_16x16x32_bf16 v[62:65], v[90:93], v[164:167], v[62:65]
	v_mfma_f32_16x16x32_bf16 v[58:61], v[100:103], v[164:167], v[58:61]
	v_mfma_f32_16x16x32_bf16 v[46:49], v[90:93], v[172:175], v[46:49]
	v_mfma_f32_16x16x32_bf16 v[42:45], v[100:103], v[172:175], v[42:45]
	v_mfma_f32_16x16x32_bf16 v[30:33], v[90:93], v[180:183], v[30:33]
	v_mfma_f32_16x16x32_bf16 v[26:29], v[100:103], v[180:183], v[26:29]
	v_mfma_f32_16x16x32_bf16 v[14:17], v[90:93], v[188:191], v[14:17]
	v_mfma_f32_16x16x32_bf16 v[10:13], v[100:103], v[188:191], v[10:13]
	v_mfma_f32_16x16x32_bf16 v[62:65], v[94:97], v[168:171], v[62:65]
	v_mfma_f32_16x16x32_bf16 v[58:61], v[104:107], v[168:171], v[58:61]
	v_mfma_f32_16x16x32_bf16 v[46:49], v[94:97], v[176:179], v[46:49]
	v_mfma_f32_16x16x32_bf16 v[42:45], v[104:107], v[176:179], v[42:45]
	v_mfma_f32_16x16x32_bf16 v[30:33], v[94:97], v[184:187], v[30:33]
	v_mfma_f32_16x16x32_bf16 v[26:29], v[104:107], v[184:187], v[26:29]
	v_mfma_f32_16x16x32_bf16 v[14:17], v[94:97], v[192:195], v[14:17]
	v_mfma_f32_16x16x32_bf16 v[10:13], v[104:107], v[192:195], v[10:13]
	s_setprio 0
	s_setprio 1
	v_mfma_f32_16x16x32_bf16 v[54:57], v[108:111], v[164:167], v[54:57]
	v_mfma_f32_16x16x32_bf16 v[50:53], v[120:123], v[164:167], v[50:53]
	v_mfma_f32_16x16x32_bf16 v[38:41], v[108:111], v[172:175], v[38:41]
	v_mfma_f32_16x16x32_bf16 v[34:37], v[120:123], v[172:175], v[34:37]
	v_mfma_f32_16x16x32_bf16 v[22:25], v[108:111], v[180:183], v[22:25]
	v_mfma_f32_16x16x32_bf16 v[18:21], v[120:123], v[180:183], v[18:21]
	v_mfma_f32_16x16x32_bf16 v[6:9], v[108:111], v[188:191], v[6:9]
	v_mfma_f32_16x16x32_bf16 v[2:5], v[120:123], v[188:191], v[2:5]
	v_mfma_f32_16x16x32_bf16 v[54:57], v[112:115], v[168:171], v[54:57]
	v_mfma_f32_16x16x32_bf16 v[50:53], v[128:131], v[168:171], v[50:53]
	v_mfma_f32_16x16x32_bf16 v[38:41], v[112:115], v[176:179], v[38:41]
	v_mfma_f32_16x16x32_bf16 v[34:37], v[128:131], v[176:179], v[34:37]
	v_mfma_f32_16x16x32_bf16 v[22:25], v[112:115], v[184:187], v[22:25]
	v_mfma_f32_16x16x32_bf16 v[18:21], v[128:131], v[184:187], v[18:21]
	v_mfma_f32_16x16x32_bf16 v[6:9], v[112:115], v[192:195], v[6:9]
	v_mfma_f32_16x16x32_bf16 v[2:5], v[128:131], v[192:195], v[2:5]
	s_setprio 0
	s_barrier
	s_add_i32 s6, 0, 0x18000
	s_add_i32 s7, 0, 0x1c000
	v_add_u32_e32 v104, s6, v239
	v_add_u32_e32 v128, s7, v239
	ds_read_b128 v[90:93], v104
	ds_read_b128 v[94:97], v104 offset:1024
	ds_read_b128 v[100:103], v104 offset:2048
	ds_read_b128 v[104:107], v104 offset:3072
	ds_read_b128 v[108:111], v128
	ds_read_b128 v[112:115], v128 offset:1024
	ds_read_b128 v[120:123], v128 offset:2048
	ds_read_b128 v[128:131], v128 offset:3072
	s_add_u32 s4, s74, 0x40000
	s_addc_u32 s5, s75, 0
	v_lshl_add_u64 v[214:215], s[4:5], 0, v[98:99]
	s_add_i32 m0, s44, 0x4000
	ds_read_b128 v[164:167], v241 offset:32768
	ds_read_b128 v[168:171], v241 offset:33792
	ds_read_b128 v[172:175], v241 offset:34816
	ds_read_b128 v[176:179], v241 offset:35840
	ds_read_b128 v[180:183], v241 offset:36864
	ds_read_b128 v[184:187], v241 offset:37888
	ds_read_b128 v[188:191], v241 offset:38912
	ds_read_b128 v[192:195], v241 offset:39936
	global_load_lds_dwordx4 v[214:215], off
	v_lshl_add_u64 v[214:215], s[4:5], 0, v[206:207]
	s_add_i32 m0, s44, 0x6000
	s_nop 0
	global_load_lds_dwordx4 v[214:215], off
	s_waitcnt vmcnt(8)
	s_waitcnt lgkmcnt(0)
	s_barrier
	s_setprio 1
	s_waitcnt lgkmcnt(0)
	v_mfma_f32_16x16x32_bf16 v[160:163], v[90:93], v[164:167], v[160:163]
	v_mfma_f32_16x16x32_bf16 v[156:159], v[100:103], v[164:167], v[156:159]
	v_mfma_f32_16x16x32_bf16 v[144:147], v[90:93], v[172:175], v[144:147]
	v_mfma_f32_16x16x32_bf16 v[140:143], v[100:103], v[172:175], v[140:143]
	v_mfma_f32_16x16x32_bf16 v[124:127], v[90:93], v[180:183], v[124:127]
	v_mfma_f32_16x16x32_bf16 v[116:119], v[100:103], v[180:183], v[116:119]
	v_mfma_f32_16x16x32_bf16 v[78:81], v[90:93], v[188:191], v[78:81]
	v_mfma_f32_16x16x32_bf16 v[74:77], v[100:103], v[188:191], v[74:77]
	v_mfma_f32_16x16x32_bf16 v[160:163], v[94:97], v[168:171], v[160:163]
	v_mfma_f32_16x16x32_bf16 v[156:159], v[104:107], v[168:171], v[156:159]
	v_mfma_f32_16x16x32_bf16 v[144:147], v[94:97], v[176:179], v[144:147]
	v_mfma_f32_16x16x32_bf16 v[140:143], v[104:107], v[176:179], v[140:143]
	v_mfma_f32_16x16x32_bf16 v[124:127], v[94:97], v[184:187], v[124:127]
	v_mfma_f32_16x16x32_bf16 v[116:119], v[104:107], v[184:187], v[116:119]
	v_mfma_f32_16x16x32_bf16 v[78:81], v[94:97], v[192:195], v[78:81]
	v_mfma_f32_16x16x32_bf16 v[74:77], v[104:107], v[192:195], v[74:77]
	s_setprio 0
	s_setprio 1
	v_mfma_f32_16x16x32_bf16 v[152:155], v[108:111], v[164:167], v[152:155]
	v_mfma_f32_16x16x32_bf16 v[148:151], v[120:123], v[164:167], v[148:151]
	v_mfma_f32_16x16x32_bf16 v[136:139], v[108:111], v[172:175], v[136:139]
	v_mfma_f32_16x16x32_bf16 v[132:135], v[120:123], v[172:175], v[132:135]
	v_mfma_f32_16x16x32_bf16 v[86:89], v[108:111], v[180:183], v[86:89]
	v_mfma_f32_16x16x32_bf16 v[82:85], v[120:123], v[180:183], v[82:85]
	v_mfma_f32_16x16x32_bf16 v[70:73], v[108:111], v[188:191], v[70:73]
	v_mfma_f32_16x16x32_bf16 v[66:69], v[120:123], v[188:191], v[66:69]
	v_mfma_f32_16x16x32_bf16 v[152:155], v[112:115], v[168:171], v[152:155]
	v_mfma_f32_16x16x32_bf16 v[148:151], v[128:131], v[168:171], v[148:151]
	v_mfma_f32_16x16x32_bf16 v[136:139], v[112:115], v[176:179], v[136:139]
	v_mfma_f32_16x16x32_bf16 v[132:135], v[128:131], v[176:179], v[132:135]
	v_mfma_f32_16x16x32_bf16 v[86:89], v[112:115], v[184:187], v[86:89]
	v_mfma_f32_16x16x32_bf16 v[82:85], v[128:131], v[184:187], v[82:85]
	v_mfma_f32_16x16x32_bf16 v[70:73], v[112:115], v[192:195], v[70:73]
	v_mfma_f32_16x16x32_bf16 v[66:69], v[128:131], v[192:195], v[66:69]
	s_setprio 0
	s_barrier
	s_add_i32 s4, s6, s91
	v_lshl_add_u64 v[200:201], v[200:201], 0, s[42:43]
	s_mov_b32 m0, s4
	ds_read_b128 v[164:167], v241 offset:49152
	ds_read_b128 v[168:171], v241 offset:50176
	ds_read_b128 v[172:175], v241 offset:51200
	ds_read_b128 v[176:179], v241 offset:52224
	ds_read_b128 v[180:183], v241 offset:53248
	ds_read_b128 v[184:187], v241 offset:54272
	ds_read_b128 v[188:191], v241 offset:55296
	ds_read_b128 v[192:195], v241 offset:56320
	global_load_lds_dwordx4 v[200:201], off
	s_add_i32 m0, s4, 0x2000
	s_add_u32 s4, s70, 0x40080
	v_lshl_add_u64 v[200:201], v[202:203], 0, s[42:43]
	s_addc_u32 s5, s71, 0
	s_add_i32 s6, s7, s91
	global_load_lds_dwordx4 v[200:201], off
	v_lshl_add_u64 v[200:201], s[4:5], 0, v[204:205]
	s_mov_b32 m0, s6
	s_nop 0
	global_load_lds_dwordx4 v[200:201], off
	v_lshl_add_u64 v[200:201], s[4:5], 0, v[208:209]
	s_add_i32 m0, s6, 0x2000
	s_nop 0
	global_load_lds_dwordx4 v[200:201], off
	v_lshl_add_u64 v[200:201], v[210:211], 0, s[42:43]
	s_add_i32 m0, s44, 0x8000
	s_nop 0
	global_load_lds_dwordx4 v[200:201], off
	v_lshl_add_u64 v[200:201], v[212:213], 0, s[42:43]
	s_add_i32 m0, s44, 0xa000
	s_nop 0
	global_load_lds_dwordx4 v[200:201], off
	s_waitcnt vmcnt(8)
	s_waitcnt lgkmcnt(0)
	s_barrier
	s_setprio 1
	s_waitcnt lgkmcnt(0)
	v_mfma_f32_16x16x32_bf16 v[62:65], v[90:93], v[164:167], v[62:65]
	v_mfma_f32_16x16x32_bf16 v[58:61], v[100:103], v[164:167], v[58:61]
	v_mfma_f32_16x16x32_bf16 v[46:49], v[90:93], v[172:175], v[46:49]
	v_mfma_f32_16x16x32_bf16 v[42:45], v[100:103], v[172:175], v[42:45]
	v_mfma_f32_16x16x32_bf16 v[30:33], v[90:93], v[180:183], v[30:33]
	v_mfma_f32_16x16x32_bf16 v[26:29], v[100:103], v[180:183], v[26:29]
	v_mfma_f32_16x16x32_bf16 v[14:17], v[90:93], v[188:191], v[14:17]
	v_mfma_f32_16x16x32_bf16 v[10:13], v[100:103], v[188:191], v[10:13]
	v_mfma_f32_16x16x32_bf16 v[62:65], v[94:97], v[168:171], v[62:65]
	v_mfma_f32_16x16x32_bf16 v[58:61], v[104:107], v[168:171], v[58:61]
	v_mfma_f32_16x16x32_bf16 v[46:49], v[94:97], v[176:179], v[46:49]
	v_mfma_f32_16x16x32_bf16 v[42:45], v[104:107], v[176:179], v[42:45]
	v_mfma_f32_16x16x32_bf16 v[30:33], v[94:97], v[184:187], v[30:33]
	v_mfma_f32_16x16x32_bf16 v[26:29], v[104:107], v[184:187], v[26:29]
	v_mfma_f32_16x16x32_bf16 v[14:17], v[94:97], v[192:195], v[14:17]
	v_mfma_f32_16x16x32_bf16 v[10:13], v[104:107], v[192:195], v[10:13]
	s_setprio 0
	s_setprio 1
	v_mfma_f32_16x16x32_bf16 v[54:57], v[108:111], v[164:167], v[54:57]
	v_mfma_f32_16x16x32_bf16 v[50:53], v[120:123], v[164:167], v[50:53]
	v_mfma_f32_16x16x32_bf16 v[38:41], v[108:111], v[172:175], v[38:41]
	v_mfma_f32_16x16x32_bf16 v[34:37], v[120:123], v[172:175], v[34:37]
	v_mfma_f32_16x16x32_bf16 v[22:25], v[108:111], v[180:183], v[22:25]
	v_mfma_f32_16x16x32_bf16 v[18:21], v[120:123], v[180:183], v[18:21]
	v_mfma_f32_16x16x32_bf16 v[6:9], v[108:111], v[188:191], v[6:9]
	v_mfma_f32_16x16x32_bf16 v[2:5], v[120:123], v[188:191], v[2:5]
	v_mfma_f32_16x16x32_bf16 v[54:57], v[112:115], v[168:171], v[54:57]
	v_mfma_f32_16x16x32_bf16 v[50:53], v[128:131], v[168:171], v[50:53]
	v_mfma_f32_16x16x32_bf16 v[38:41], v[112:115], v[176:179], v[38:41]
	v_mfma_f32_16x16x32_bf16 v[34:37], v[128:131], v[176:179], v[34:37]
	v_mfma_f32_16x16x32_bf16 v[22:25], v[112:115], v[184:187], v[22:25]
	v_mfma_f32_16x16x32_bf16 v[18:21], v[128:131], v[184:187], v[18:21]
	v_mfma_f32_16x16x32_bf16 v[6:9], v[112:115], v[192:195], v[6:9]
	v_mfma_f32_16x16x32_bf16 v[2:5], v[128:131], v[192:195], v[2:5]
	s_setprio 0
	s_barrier
	s_mov_b32 s100, 0
	s_add_i32 s97, s97, 2
	s_add_u32 s68, s68, 0x100
	s_addc_u32 s69, s69, 0
	s_add_u32 vcc_hi, vcc_hi, 0x100
	s_addc_u32 s96, s96, 0
	s_cmp_gt_u32 s97, 13
	s_cbranch_scc0 .LBB0_864
	s_mov_b32 s100, 1
	s_and_b64 vcc, exec, s[12:13]
	s_cbranch_vccz .LBB0_867
	s_barrier

.LBB0_908:
	s_add_u32 s4, s56, 0xfffc0080
	s_addc_u32 s5, s57, -1
	s_add_i32 s45, 0, 0x10000
	s_cmp_eq_u32 s96, 12
	s_cselect_b32 s71, s21, s5
	s_cselect_b32 s70, s93, s4
	s_cselect_b32 s69, s15, vcc_lo
	s_cselect_b32 s68, s94, s95
	s_add_i32 s97, 0, 0x14000
	v_add_u32_e32 v104, s45, v223
	v_add_u32_e32 v124, s97, v223
	ds_read_b128 v[86:89], v104
	ds_read_b128 v[90:93], v104 offset:1024
	ds_read_b128 v[100:103], v104 offset:2048
	ds_read_b128 v[104:107], v104 offset:3072
	ds_read_b128 v[108:111], v124
	ds_read_b128 v[112:115], v124 offset:1024
	ds_read_b128 v[116:119], v124 offset:2048
	ds_read_b128 v[124:127], v124 offset:3072
	s_add_i32 s44, s74, 0
	v_lshl_add_u64 v[200:201], s[56:57], 0, v[98:99]
	s_add_i32 m0, s44, 0xc000
	ds_read_b128 v[164:167], v225
	ds_read_b128 v[168:171], v225 offset:1024
	ds_read_b128 v[172:175], v225 offset:2048
	ds_read_b128 v[176:179], v225 offset:3072
	ds_read_b128 v[180:183], v225 offset:4096
	ds_read_b128 v[184:187], v225 offset:5120
	ds_read_b128 v[188:191], v225 offset:6144
	ds_read_b128 v[192:195], v225 offset:7168
	global_load_lds_dwordx4 v[200:201], off
	v_lshl_add_u64 v[200:201], s[56:57], 0, v[206:207]
	s_add_i32 m0, s44, 0xe000
	s_nop 0
	global_load_lds_dwordx4 v[200:201], off
	s_cmp_eq_u32 s100, 1
	s_cbranch_scc1 .Lmy_sk5
	s_waitcnt vmcnt(8)
.Lmy_sk5:
	s_waitcnt lgkmcnt(0)
	s_barrier
	s_setprio 1
	s_waitcnt lgkmcnt(0)
	v_mfma_f32_16x16x32_bf16 v[160:163], v[86:89], v[164:167], v[160:163]
	v_mfma_f32_16x16x32_bf16 v[156:159], v[100:103], v[164:167], v[156:159]
	v_mfma_f32_16x16x32_bf16 v[144:147], v[86:89], v[172:175], v[144:147]
	v_mfma_f32_16x16x32_bf16 v[140:143], v[100:103], v[172:175], v[140:143]
	v_mfma_f32_16x16x32_bf16 v[128:131], v[86:89], v[180:183], v[128:131]
	v_mfma_f32_16x16x32_bf16 v[120:123], v[100:103], v[180:183], v[120:123]
	v_mfma_f32_16x16x32_bf16 v[78:81], v[86:89], v[188:191], v[78:81]
	v_mfma_f32_16x16x32_bf16 v[74:77], v[100:103], v[188:191], v[74:77]
	v_mfma_f32_16x16x32_bf16 v[160:163], v[90:93], v[168:171], v[160:163]
	v_mfma_f32_16x16x32_bf16 v[156:159], v[104:107], v[168:171], v[156:159]
	v_mfma_f32_16x16x32_bf16 v[144:147], v[90:93], v[176:179], v[144:147]
	v_mfma_f32_16x16x32_bf16 v[140:143], v[104:107], v[176:179], v[140:143]
	v_mfma_f32_16x16x32_bf16 v[128:131], v[90:93], v[184:187], v[128:131]
	v_mfma_f32_16x16x32_bf16 v[120:123], v[104:107], v[184:187], v[120:123]
	v_mfma_f32_16x16x32_bf16 v[78:81], v[90:93], v[192:195], v[78:81]
	v_mfma_f32_16x16x32_bf16 v[74:77], v[104:107], v[192:195], v[74:77]
	s_setprio 0
	s_setprio 1
	v_mfma_f32_16x16x32_bf16 v[152:155], v[108:111], v[164:167], v[152:155]
	v_mfma_f32_16x16x32_bf16 v[148:151], v[116:119], v[164:167], v[148:151]
	v_mfma_f32_16x16x32_bf16 v[136:139], v[108:111], v[172:175], v[136:139]
	v_mfma_f32_16x16x32_bf16 v[132:135], v[116:119], v[172:175], v[132:135]
	v_mfma_f32_16x16x32_bf16 v[94:97], v[108:111], v[180:183], v[94:97]
	v_mfma_f32_16x16x32_bf16 v[82:85], v[116:119], v[180:183], v[82:85]
	v_mfma_f32_16x16x32_bf16 v[70:73], v[108:111], v[188:191], v[70:73]
	v_mfma_f32_16x16x32_bf16 v[66:69], v[116:119], v[188:191], v[66:69]
	v_mfma_f32_16x16x32_bf16 v[152:155], v[112:115], v[168:171], v[152:155]
	v_mfma_f32_16x16x32_bf16 v[148:151], v[124:127], v[168:171], v[148:151]
	v_mfma_f32_16x16x32_bf16 v[136:139], v[112:115], v[176:179], v[136:139]
	v_mfma_f32_16x16x32_bf16 v[132:135], v[124:127], v[176:179], v[132:135]
	v_mfma_f32_16x16x32_bf16 v[94:97], v[112:115], v[184:187], v[94:97]
	v_mfma_f32_16x16x32_bf16 v[82:85], v[124:127], v[184:187], v[82:85]
	v_mfma_f32_16x16x32_bf16 v[70:73], v[112:115], v[192:195], v[70:73]
	v_mfma_f32_16x16x32_bf16 v[66:69], v[124:127], v[192:195], v[66:69]
	s_setprio 0
	s_barrier
	s_add_i32 s4, s45, s74
	v_lshl_add_u64 v[200:201], s[68:69], 0, v[204:205]
	s_mov_b32 m0, s4
	ds_read_b128 v[164:167], v225 offset:16384
	ds_read_b128 v[168:171], v225 offset:17408
	ds_read_b128 v[172:175], v225 offset:18432
	ds_read_b128 v[176:179], v225 offset:19456
	ds_read_b128 v[180:183], v225 offset:20480
	ds_read_b128 v[184:187], v225 offset:21504
	ds_read_b128 v[188:191], v225 offset:22528
	ds_read_b128 v[192:195], v225 offset:23552
	global_load_lds_dwordx4 v[200:201], off
	s_add_i32 m0, s4, 0x2000
	s_add_u32 s4, s68, 0x40000
	v_lshl_add_u64 v[202:203], s[68:69], 0, v[208:209]
	s_addc_u32 s5, s69, 0
	s_add_i32 s45, s97, s74
	global_load_lds_dwordx4 v[202:203], off
	v_lshl_add_u64 v[210:211], s[4:5], 0, v[204:205]
	s_mov_b32 m0, s45
	v_lshl_add_u64 v[212:213], s[70:71], 0, v[206:207]
	global_load_lds_dwordx4 v[210:211], off
	v_lshl_add_u64 v[210:211], s[4:5], 0, v[208:209]
	s_add_i32 m0, s45, 0x2000
	s_nop 0
	global_load_lds_dwordx4 v[210:211], off
	v_lshl_add_u64 v[210:211], s[70:71], 0, v[98:99]
	s_mov_b32 m0, s44
	s_nop 0
	global_load_lds_dwordx4 v[210:211], off
	s_add_i32 m0, s44, 0x2000
	s_nop 0
	global_load_lds_dwordx4 v[212:213], off
	s_cmp_eq_u32 s100, 1
	s_cbranch_scc1 .Lmy_sk6
	s_waitcnt vmcnt(8)
.Lmy_sk6:
	s_waitcnt lgkmcnt(0)
	s_barrier
	s_setprio 1
	s_waitcnt lgkmcnt(0)
	v_mfma_f32_16x16x32_bf16 v[62:65], v[86:89], v[164:167], v[62:65]
	v_mfma_f32_16x16x32_bf16 v[58:61], v[100:103], v[164:167], v[58:61]
	v_mfma_f32_16x16x32_bf16 v[46:49], v[86:89], v[172:175], v[46:49]
	v_mfma_f32_16x16x32_bf16 v[42:45], v[100:103], v[172:175], v[42:45]
	v_mfma_f32_16x16x32_bf16 v[30:33], v[86:89], v[180:183], v[30:33]
	v_mfma_f32_16x16x32_bf16 v[26:29], v[100:103], v[180:183], v[26:29]
	v_mfma_f32_16x16x32_bf16 v[14:17], v[86:89], v[188:191], v[14:17]
	v_mfma_f32_16x16x32_bf16 v[10:13], v[100:103], v[188:191], v[10:13]
	v_mfma_f32_16x16x32_bf16 v[62:65], v[90:93], v[168:171], v[62:65]
	v_mfma_f32_16x16x32_bf16 v[58:61], v[104:107], v[168:171], v[58:61]
	v_mfma_f32_16x16x32_bf16 v[46:49], v[90:93], v[176:179], v[46:49]
	v_mfma_f32_16x16x32_bf16 v[42:45], v[104:107], v[176:179], v[42:45]
	v_mfma_f32_16x16x32_bf16 v[30:33], v[90:93], v[184:187], v[30:33]
	v_mfma_f32_16x16x32_bf16 v[26:29], v[104:107], v[184:187], v[26:29]
	v_mfma_f32_16x16x32_bf16 v[14:17], v[90:93], v[192:195], v[14:17]
	v_mfma_f32_16x16x32_bf16 v[10:13], v[104:107], v[192:195], v[10:13]
	s_setprio 0
	s_setprio 1
	v_mfma_f32_16x16x32_bf16 v[54:57], v[108:111], v[164:167], v[54:57]
	v_mfma_f32_16x16x32_bf16 v[50:53], v[116:119], v[164:167], v[50:53]
	v_mfma_f32_16x16x32_bf16 v[38:41], v[108:111], v[172:175], v[38:41]
	v_mfma_f32_16x16x32_bf16 v[34:37], v[116:119], v[172:175], v[34:37]
	v_mfma_f32_16x16x32_bf16 v[22:25], v[108:111], v[180:183], v[22:25]
	v_mfma_f32_16x16x32_bf16 v[18:21], v[116:119], v[180:183], v[18:21]
	v_mfma_f32_16x16x32_bf16 v[6:9], v[108:111], v[188:191], v[6:9]
	v_mfma_f32_16x16x32_bf16 v[2:5], v[116:119], v[188:191], v[2:5]
	v_mfma_f32_16x16x32_bf16 v[54:57], v[112:115], v[168:171], v[54:57]
	v_mfma_f32_16x16x32_bf16 v[50:53], v[124:127], v[168:171], v[50:53]
	v_mfma_f32_16x16x32_bf16 v[38:41], v[112:115], v[176:179], v[38:41]
	v_mfma_f32_16x16x32_bf16 v[34:37], v[124:127], v[176:179], v[34:37]
	v_mfma_f32_16x16x32_bf16 v[22:25], v[112:115], v[184:187], v[22:25]
	v_mfma_f32_16x16x32_bf16 v[18:21], v[124:127], v[184:187], v[18:21]
	v_mfma_f32_16x16x32_bf16 v[6:9], v[112:115], v[192:195], v[6:9]
	v_mfma_f32_16x16x32_bf16 v[2:5], v[124:127], v[192:195], v[2:5]
	s_setprio 0
	s_barrier
	s_add_i32 s45, 0, 0x18000
	s_add_i32 s97, 0, 0x1c000
	v_add_u32_e32 v104, s45, v223
	v_add_u32_e32 v124, s97, v223
	ds_read_b128 v[86:89], v104
	ds_read_b128 v[90:93], v104 offset:1024
	ds_read_b128 v[100:103], v104 offset:2048
	ds_read_b128 v[104:107], v104 offset:3072
	ds_read_b128 v[108:111], v124
	ds_read_b128 v[112:115], v124 offset:1024
	ds_read_b128 v[116:119], v124 offset:2048
	ds_read_b128 v[124:127], v124 offset:3072
	s_add_u32 s4, s70, 0x40000
	s_addc_u32 s5, s71, 0
	v_lshl_add_u64 v[214:215], s[4:5], 0, v[98:99]
	s_add_i32 m0, s44, 0x4000
	ds_read_b128 v[164:167], v225 offset:32768
	ds_read_b128 v[168:171], v225 offset:33792
	ds_read_b128 v[172:175], v225 offset:34816
	ds_read_b128 v[176:179], v225 offset:35840
	ds_read_b128 v[180:183], v225 offset:36864
	ds_read_b128 v[184:187], v225 offset:37888
	ds_read_b128 v[188:191], v225 offset:38912
	ds_read_b128 v[192:195], v225 offset:39936
	global_load_lds_dwordx4 v[214:215], off
	v_lshl_add_u64 v[214:215], s[4:5], 0, v[206:207]
	s_add_i32 m0, s44, 0x6000
	s_nop 0
	global_load_lds_dwordx4 v[214:215], off
	s_waitcnt vmcnt(8)
	s_waitcnt lgkmcnt(0)
	s_barrier
	s_setprio 1
	s_waitcnt lgkmcnt(0)
	v_mfma_f32_16x16x32_bf16 v[160:163], v[86:89], v[164:167], v[160:163]
	v_mfma_f32_16x16x32_bf16 v[156:159], v[100:103], v[164:167], v[156:159]
	v_mfma_f32_16x16x32_bf16 v[144:147], v[86:89], v[172:175], v[144:147]
	v_mfma_f32_16x16x32_bf16 v[140:143], v[100:103], v[172:175], v[140:143]
	v_mfma_f32_16x16x32_bf16 v[128:131], v[86:89], v[180:183], v[128:131]
	v_mfma_f32_16x16x32_bf16 v[120:123], v[100:103], v[180:183], v[120:123]
	v_mfma_f32_16x16x32_bf16 v[78:81], v[86:89], v[188:191], v[78:81]
	v_mfma_f32_16x16x32_bf16 v[74:77], v[100:103], v[188:191], v[74:77]
	v_mfma_f32_16x16x32_bf16 v[160:163], v[90:93], v[168:171], v[160:163]
	v_mfma_f32_16x16x32_bf16 v[156:159], v[104:107], v[168:171], v[156:159]
	v_mfma_f32_16x16x32_bf16 v[144:147], v[90:93], v[176:179], v[144:147]
	v_mfma_f32_16x16x32_bf16 v[140:143], v[104:107], v[176:179], v[140:143]
	v_mfma_f32_16x16x32_bf16 v[128:131], v[90:93], v[184:187], v[128:131]
	v_mfma_f32_16x16x32_bf16 v[120:123], v[104:107], v[184:187], v[120:123]
	v_mfma_f32_16x16x32_bf16 v[78:81], v[90:93], v[192:195], v[78:81]
	v_mfma_f32_16x16x32_bf16 v[74:77], v[104:107], v[192:195], v[74:77]
	s_setprio 0
	s_setprio 1
	v_mfma_f32_16x16x32_bf16 v[152:155], v[108:111], v[164:167], v[152:155]
	v_mfma_f32_16x16x32_bf16 v[148:151], v[116:119], v[164:167], v[148:151]
	v_mfma_f32_16x16x32_bf16 v[136:139], v[108:111], v[172:175], v[136:139]
	v_mfma_f32_16x16x32_bf16 v[132:135], v[116:119], v[172:175], v[132:135]
	v_mfma_f32_16x16x32_bf16 v[94:97], v[108:111], v[180:183], v[94:97]
	v_mfma_f32_16x16x32_bf16 v[82:85], v[116:119], v[180:183], v[82:85]
	v_mfma_f32_16x16x32_bf16 v[70:73], v[108:111], v[188:191], v[70:73]
	v_mfma_f32_16x16x32_bf16 v[66:69], v[116:119], v[188:191], v[66:69]
	v_mfma_f32_16x16x32_bf16 v[152:155], v[112:115], v[168:171], v[152:155]
	v_mfma_f32_16x16x32_bf16 v[148:151], v[124:127], v[168:171], v[148:151]
	v_mfma_f32_16x16x32_bf16 v[136:139], v[112:115], v[176:179], v[136:139]
	v_mfma_f32_16x16x32_bf16 v[132:135], v[124:127], v[176:179], v[132:135]
	v_mfma_f32_16x16x32_bf16 v[94:97], v[112:115], v[184:187], v[94:97]
	v_mfma_f32_16x16x32_bf16 v[82:85], v[124:127], v[184:187], v[82:85]
	v_mfma_f32_16x16x32_bf16 v[70:73], v[112:115], v[192:195], v[70:73]
	v_mfma_f32_16x16x32_bf16 v[66:69], v[124:127], v[192:195], v[66:69]
	s_setprio 0
	s_barrier
	s_add_i32 s4, s45, s74
	v_lshl_add_u64 v[200:201], v[200:201], 0, s[42:43]
	s_mov_b32 m0, s4
	ds_read_b128 v[164:167], v225 offset:49152
	ds_read_b128 v[168:171], v225 offset:50176
	ds_read_b128 v[172:175], v225 offset:51200
	ds_read_b128 v[176:179], v225 offset:52224
	ds_read_b128 v[180:183], v225 offset:53248
	ds_read_b128 v[184:187], v225 offset:54272
	ds_read_b128 v[188:191], v225 offset:55296
	ds_read_b128 v[192:195], v225 offset:56320
	global_load_lds_dwordx4 v[200:201], off
	s_add_i32 m0, s4, 0x2000
	s_add_u32 s4, s68, 0x40080
	v_lshl_add_u64 v[200:201], v[202:203], 0, s[42:43]
	s_addc_u32 s5, s69, 0
	s_add_i32 s45, s97, s74
	global_load_lds_dwordx4 v[200:201], off
	v_lshl_add_u64 v[200:201], s[4:5], 0, v[204:205]
	s_mov_b32 m0, s45
	s_nop 0
	global_load_lds_dwordx4 v[200:201], off
	v_lshl_add_u64 v[200:201], s[4:5], 0, v[208:209]
	s_add_i32 m0, s45, 0x2000
	s_nop 0
	global_load_lds_dwordx4 v[200:201], off
	v_lshl_add_u64 v[200:201], v[210:211], 0, s[42:43]
	s_add_i32 m0, s44, 0x8000
	s_nop 0
	global_load_lds_dwordx4 v[200:201], off
	v_lshl_add_u64 v[200:201], v[212:213], 0, s[42:43]
	s_add_i32 m0, s44, 0xa000
	s_nop 0
	global_load_lds_dwordx4 v[200:201], off
	s_waitcnt vmcnt(8)
	s_waitcnt lgkmcnt(0)
	s_barrier
	s_setprio 1
	s_waitcnt lgkmcnt(0)
	v_mfma_f32_16x16x32_bf16 v[62:65], v[86:89], v[164:167], v[62:65]
	v_mfma_f32_16x16x32_bf16 v[58:61], v[100:103], v[164:167], v[58:61]
	v_mfma_f32_16x16x32_bf16 v[46:49], v[86:89], v[172:175], v[46:49]
	v_mfma_f32_16x16x32_bf16 v[42:45], v[100:103], v[172:175], v[42:45]
	v_mfma_f32_16x16x32_bf16 v[30:33], v[86:89], v[180:183], v[30:33]
	v_mfma_f32_16x16x32_bf16 v[26:29], v[100:103], v[180:183], v[26:29]
	v_mfma_f32_16x16x32_bf16 v[14:17], v[86:89], v[188:191], v[14:17]
	v_mfma_f32_16x16x32_bf16 v[10:13], v[100:103], v[188:191], v[10:13]
	v_mfma_f32_16x16x32_bf16 v[62:65], v[90:93], v[168:171], v[62:65]
	v_mfma_f32_16x16x32_bf16 v[58:61], v[104:107], v[168:171], v[58:61]
	v_mfma_f32_16x16x32_bf16 v[46:49], v[90:93], v[176:179], v[46:49]
	v_mfma_f32_16x16x32_bf16 v[42:45], v[104:107], v[176:179], v[42:45]
	v_mfma_f32_16x16x32_bf16 v[30:33], v[90:93], v[184:187], v[30:33]
	v_mfma_f32_16x16x32_bf16 v[26:29], v[104:107], v[184:187], v[26:29]
	v_mfma_f32_16x16x32_bf16 v[14:17], v[90:93], v[192:195], v[14:17]
	v_mfma_f32_16x16x32_bf16 v[10:13], v[104:107], v[192:195], v[10:13]
	s_setprio 0
	s_setprio 1
	v_mfma_f32_16x16x32_bf16 v[54:57], v[108:111], v[164:167], v[54:57]
	v_mfma_f32_16x16x32_bf16 v[50:53], v[116:119], v[164:167], v[50:53]
	v_mfma_f32_16x16x32_bf16 v[38:41], v[108:111], v[172:175], v[38:41]
	v_mfma_f32_16x16x32_bf16 v[34:37], v[116:119], v[172:175], v[34:37]
	v_mfma_f32_16x16x32_bf16 v[22:25], v[108:111], v[180:183], v[22:25]
	v_mfma_f32_16x16x32_bf16 v[18:21], v[116:119], v[180:183], v[18:21]
	v_mfma_f32_16x16x32_bf16 v[6:9], v[108:111], v[188:191], v[6:9]
	v_mfma_f32_16x16x32_bf16 v[2:5], v[116:119], v[188:191], v[2:5]
	v_mfma_f32_16x16x32_bf16 v[54:57], v[112:115], v[168:171], v[54:57]
	v_mfma_f32_16x16x32_bf16 v[50:53], v[124:127], v[168:171], v[50:53]
	v_mfma_f32_16x16x32_bf16 v[38:41], v[112:115], v[176:179], v[38:41]
	v_mfma_f32_16x16x32_bf16 v[34:37], v[124:127], v[176:179], v[34:37]
	v_mfma_f32_16x16x32_bf16 v[22:25], v[112:115], v[184:187], v[22:25]
	v_mfma_f32_16x16x32_bf16 v[18:21], v[124:127], v[184:187], v[18:21]
	v_mfma_f32_16x16x32_bf16 v[6:9], v[112:115], v[192:195], v[6:9]
	v_mfma_f32_16x16x32_bf16 v[2:5], v[124:127], v[192:195], v[2:5]
	s_setprio 0
	s_barrier
	s_mov_b32 s100, 0
	s_add_i32 s96, s96, 2
	s_add_u32 s56, s56, 0x100
	s_addc_u32 s57, s57, 0
	s_add_u32 s95, s95, 0x100
	s_addc_u32 vcc_lo, vcc_lo, 0
	s_cmp_gt_u32 s96, 13
	s_cbranch_scc0 .LBB0_908
	s_mov_b32 s100, 1
	v_mov_b32_e32 v196, 0x2d00
	v_mov_b32_e32 v231, 0x2400
	v_mov_b32_e32 v228, 0x1b00
	s_and_b64 vcc, exec, s[0:1]
	s_movk_i32 s21, 0x4000
	s_cbranch_vccz .LBB0_911
	s_barrier

.LBB0_1011:
	s_add_u32 s4, s40, 0xfffc0080
	s_addc_u32 s5, s41, -1
	s_add_i32 s6, 0, 0x10000
	s_cmp_eq_u32 s92, 12
	s_cselect_b32 s69, s21, s5
	s_cselect_b32 s68, s88, s4
	s_cselect_b32 s57, s15, s91
	s_cselect_b32 s56, s89, s90
	s_add_i32 s7, 0, 0x14000
	v_add_u32_e32 v144, s6, v189
	v_add_u32_e32 v160, s7, v189
	ds_read_b128 v[132:135], v144
	ds_read_b128 v[136:139], v144 offset:1024
	ds_read_b128 v[140:143], v144 offset:2048
	ds_read_b128 v[144:147], v144 offset:3072
	ds_read_b128 v[156:159], v160
	ds_read_b128 v[162:165], v160 offset:1024
	ds_read_b128 v[192:195], v160 offset:2048
	ds_read_b128 v[200:203], v160 offset:3072
	s_add_i32 s44, s70, 0
	v_lshl_add_u64 v[166:167], s[40:41], 0, v[98:99]
	s_add_i32 m0, s44, 0xc000
	ds_read_b128 v[204:207], v191
	ds_read_b128 v[208:211], v191 offset:1024
	ds_read_b128 v[212:215], v191 offset:2048
	ds_read_b128 v[216:219], v191 offset:3072
	ds_read_b128 v[220:223], v191 offset:4096
	ds_read_b128 v[224:227], v191 offset:5120
	ds_read_b128 v[238:241], v191 offset:6144
	ds_read_b128 v[242:245], v191 offset:7168
	global_load_lds_dwordx4 v[166:167], off
	v_lshl_add_u64 v[166:167], s[40:41], 0, v[150:151]
	s_add_i32 m0, s44, 0xe000
	s_nop 0
	global_load_lds_dwordx4 v[166:167], off
	s_cmp_eq_u32 s100, 1
	s_cbranch_scc1 .Lmy_sk7
	s_waitcnt vmcnt(8)
.Lmy_sk7:
	s_waitcnt lgkmcnt(0)
	s_barrier
	s_setprio 1
	s_waitcnt lgkmcnt(0)
	v_mfma_f32_16x16x32_bf16 v[128:131], v[132:135], v[204:207], v[128:131]
	v_mfma_f32_16x16x32_bf16 v[124:127], v[140:143], v[204:207], v[124:127]
	v_mfma_f32_16x16x32_bf16 v[112:115], v[132:135], v[212:215], v[112:115]
	v_mfma_f32_16x16x32_bf16 v[108:111], v[140:143], v[212:215], v[108:111]
	v_mfma_f32_16x16x32_bf16 v[94:97], v[132:135], v[220:223], v[94:97]
	v_mfma_f32_16x16x32_bf16 v[90:93], v[140:143], v[220:223], v[90:93]
	v_mfma_f32_16x16x32_bf16 v[78:81], v[132:135], v[238:241], v[78:81]
	v_mfma_f32_16x16x32_bf16 v[74:77], v[140:143], v[238:241], v[74:77]
	v_mfma_f32_16x16x32_bf16 v[128:131], v[136:139], v[208:211], v[128:131]
	v_mfma_f32_16x16x32_bf16 v[124:127], v[144:147], v[208:211], v[124:127]
	v_mfma_f32_16x16x32_bf16 v[112:115], v[136:139], v[216:219], v[112:115]
	v_mfma_f32_16x16x32_bf16 v[108:111], v[144:147], v[216:219], v[108:111]
	v_mfma_f32_16x16x32_bf16 v[94:97], v[136:139], v[224:227], v[94:97]
	v_mfma_f32_16x16x32_bf16 v[90:93], v[144:147], v[224:227], v[90:93]
	v_mfma_f32_16x16x32_bf16 v[78:81], v[136:139], v[242:245], v[78:81]
	v_mfma_f32_16x16x32_bf16 v[74:77], v[144:147], v[242:245], v[74:77]
	s_setprio 0
	s_setprio 1
	v_mfma_f32_16x16x32_bf16 v[120:123], v[156:159], v[204:207], v[120:123]
	v_mfma_f32_16x16x32_bf16 v[116:119], v[192:195], v[204:207], v[116:119]
	v_mfma_f32_16x16x32_bf16 v[104:107], v[156:159], v[212:215], v[104:107]
	v_mfma_f32_16x16x32_bf16 v[100:103], v[192:195], v[212:215], v[100:103]
	v_mfma_f32_16x16x32_bf16 v[86:89], v[156:159], v[220:223], v[86:89]
	v_mfma_f32_16x16x32_bf16 v[82:85], v[192:195], v[220:223], v[82:85]
	v_mfma_f32_16x16x32_bf16 v[70:73], v[156:159], v[238:241], v[70:73]
	v_mfma_f32_16x16x32_bf16 v[66:69], v[192:195], v[238:241], v[66:69]
	v_mfma_f32_16x16x32_bf16 v[120:123], v[162:165], v[208:211], v[120:123]
	v_mfma_f32_16x16x32_bf16 v[116:119], v[200:203], v[208:211], v[116:119]
	v_mfma_f32_16x16x32_bf16 v[104:107], v[162:165], v[216:219], v[104:107]
	v_mfma_f32_16x16x32_bf16 v[100:103], v[200:203], v[216:219], v[100:103]
	v_mfma_f32_16x16x32_bf16 v[86:89], v[162:165], v[224:227], v[86:89]
	v_mfma_f32_16x16x32_bf16 v[82:85], v[200:203], v[224:227], v[82:85]
	v_mfma_f32_16x16x32_bf16 v[70:73], v[162:165], v[242:245], v[70:73]
	v_mfma_f32_16x16x32_bf16 v[66:69], v[200:203], v[242:245], v[66:69]
	s_setprio 0
	s_barrier
	s_add_i32 s4, s6, s70
	v_lshl_add_u64 v[166:167], s[56:57], 0, v[148:149]
	s_mov_b32 m0, s4
	ds_read_b128 v[204:207], v191 offset:16384
	ds_read_b128 v[208:211], v191 offset:17408
	ds_read_b128 v[212:215], v191 offset:18432
	ds_read_b128 v[216:219], v191 offset:19456
	ds_read_b128 v[220:223], v191 offset:20480
	ds_read_b128 v[224:227], v191 offset:21504
	ds_read_b128 v[238:241], v191 offset:22528
	ds_read_b128 v[242:245], v191 offset:23552
	global_load_lds_dwordx4 v[166:167], off
	s_add_i32 m0, s4, 0x2000
	s_add_u32 s4, s56, 0x40000
	v_lshl_add_u64 v[170:171], s[56:57], 0, v[152:153]
	s_addc_u32 s5, s57, 0
	s_add_i32 s6, s7, s70
	global_load_lds_dwordx4 v[170:171], off
	v_lshl_add_u64 v[176:177], s[4:5], 0, v[148:149]
	s_mov_b32 m0, s6
	v_lshl_add_u64 v[180:181], s[68:69], 0, v[150:151]
	global_load_lds_dwordx4 v[176:177], off
	v_lshl_add_u64 v[176:177], s[4:5], 0, v[152:153]
	s_add_i32 m0, s6, 0x2000
	s_nop 0
	global_load_lds_dwordx4 v[176:177], off
	v_lshl_add_u64 v[176:177], s[68:69], 0, v[98:99]
	s_mov_b32 m0, s44
	s_nop 0
	global_load_lds_dwordx4 v[176:177], off
	s_add_i32 m0, s44, 0x2000
	s_nop 0
	global_load_lds_dwordx4 v[180:181], off
	s_cmp_eq_u32 s100, 1
	s_cbranch_scc1 .Lmy_sk8
	s_waitcnt vmcnt(8)
.Lmy_sk8:
	s_waitcnt lgkmcnt(0)
	s_barrier
	s_setprio 1
	s_waitcnt lgkmcnt(0)
	v_mfma_f32_16x16x32_bf16 v[62:65], v[132:135], v[204:207], v[62:65]
	v_mfma_f32_16x16x32_bf16 v[58:61], v[140:143], v[204:207], v[58:61]
	v_mfma_f32_16x16x32_bf16 v[46:49], v[132:135], v[212:215], v[46:49]
	v_mfma_f32_16x16x32_bf16 v[42:45], v[140:143], v[212:215], v[42:45]
	v_mfma_f32_16x16x32_bf16 v[30:33], v[132:135], v[220:223], v[30:33]
	v_mfma_f32_16x16x32_bf16 v[26:29], v[140:143], v[220:223], v[26:29]
	v_mfma_f32_16x16x32_bf16 v[14:17], v[132:135], v[238:241], v[14:17]
	v_mfma_f32_16x16x32_bf16 v[10:13], v[140:143], v[238:241], v[10:13]
	v_mfma_f32_16x16x32_bf16 v[62:65], v[136:139], v[208:211], v[62:65]
	v_mfma_f32_16x16x32_bf16 v[58:61], v[144:147], v[208:211], v[58:61]
	v_mfma_f32_16x16x32_bf16 v[46:49], v[136:139], v[216:219], v[46:49]
	v_mfma_f32_16x16x32_bf16 v[42:45], v[144:147], v[216:219], v[42:45]
	v_mfma_f32_16x16x32_bf16 v[30:33], v[136:139], v[224:227], v[30:33]
	v_mfma_f32_16x16x32_bf16 v[26:29], v[144:147], v[224:227], v[26:29]
	v_mfma_f32_16x16x32_bf16 v[14:17], v[136:139], v[242:245], v[14:17]
	v_mfma_f32_16x16x32_bf16 v[10:13], v[144:147], v[242:245], v[10:13]
	s_setprio 0
	s_setprio 1
	v_mfma_f32_16x16x32_bf16 v[54:57], v[156:159], v[204:207], v[54:57]
	v_mfma_f32_16x16x32_bf16 v[50:53], v[192:195], v[204:207], v[50:53]
	v_mfma_f32_16x16x32_bf16 v[38:41], v[156:159], v[212:215], v[38:41]
	v_mfma_f32_16x16x32_bf16 v[34:37], v[192:195], v[212:215], v[34:37]
	v_mfma_f32_16x16x32_bf16 v[22:25], v[156:159], v[220:223], v[22:25]
	v_mfma_f32_16x16x32_bf16 v[18:21], v[192:195], v[220:223], v[18:21]
	v_mfma_f32_16x16x32_bf16 v[6:9], v[156:159], v[238:241], v[6:9]
	v_mfma_f32_16x16x32_bf16 v[2:5], v[192:195], v[238:241], v[2:5]
	v_mfma_f32_16x16x32_bf16 v[54:57], v[162:165], v[208:211], v[54:57]
	v_mfma_f32_16x16x32_bf16 v[50:53], v[200:203], v[208:211], v[50:53]
	v_mfma_f32_16x16x32_bf16 v[38:41], v[162:165], v[216:219], v[38:41]
	v_mfma_f32_16x16x32_bf16 v[34:37], v[200:203], v[216:219], v[34:37]
	v_mfma_f32_16x16x32_bf16 v[22:25], v[162:165], v[224:227], v[22:25]
	v_mfma_f32_16x16x32_bf16 v[18:21], v[200:203], v[224:227], v[18:21]
	v_mfma_f32_16x16x32_bf16 v[6:9], v[162:165], v[242:245], v[6:9]
	v_mfma_f32_16x16x32_bf16 v[2:5], v[200:203], v[242:245], v[2:5]
	s_setprio 0
	s_barrier
	s_add_i32 s6, 0, 0x18000
	s_add_i32 s7, 0, 0x1c000
	v_add_u32_e32 v144, s6, v189
	v_add_u32_e32 v160, s7, v189
	ds_read_b128 v[132:135], v144
	ds_read_b128 v[136:139], v144 offset:1024
	ds_read_b128 v[140:143], v144 offset:2048
	ds_read_b128 v[144:147], v144 offset:3072
	ds_read_b128 v[156:159], v160
	ds_read_b128 v[162:165], v160 offset:1024
	ds_read_b128 v[192:195], v160 offset:2048
	ds_read_b128 v[200:203], v160 offset:3072
	s_add_u32 s4, s68, 0x40000
	s_addc_u32 s5, s69, 0
	v_lshl_add_u64 v[246:247], s[4:5], 0, v[98:99]
	s_add_i32 m0, s44, 0x4000
	ds_read_b128 v[204:207], v191 offset:32768
	ds_read_b128 v[208:211], v191 offset:33792
	ds_read_b128 v[212:215], v191 offset:34816
	ds_read_b128 v[216:219], v191 offset:35840
	ds_read_b128 v[220:223], v191 offset:36864
	ds_read_b128 v[224:227], v191 offset:37888
	ds_read_b128 v[238:241], v191 offset:38912
	ds_read_b128 v[242:245], v191 offset:39936
	global_load_lds_dwordx4 v[246:247], off
	v_lshl_add_u64 v[246:247], s[4:5], 0, v[150:151]
	s_add_i32 m0, s44, 0x6000
	s_nop 0
	global_load_lds_dwordx4 v[246:247], off
	s_waitcnt vmcnt(8)
	s_waitcnt lgkmcnt(0)
	s_barrier
	s_setprio 1
	s_waitcnt lgkmcnt(0)
	v_mfma_f32_16x16x32_bf16 v[128:131], v[132:135], v[204:207], v[128:131]
	v_mfma_f32_16x16x32_bf16 v[124:127], v[140:143], v[204:207], v[124:127]
	v_mfma_f32_16x16x32_bf16 v[112:115], v[132:135], v[212:215], v[112:115]
	v_mfma_f32_16x16x32_bf16 v[108:111], v[140:143], v[212:215], v[108:111]
	v_mfma_f32_16x16x32_bf16 v[94:97], v[132:135], v[220:223], v[94:97]
	v_mfma_f32_16x16x32_bf16 v[90:93], v[140:143], v[220:223], v[90:93]
	v_mfma_f32_16x16x32_bf16 v[78:81], v[132:135], v[238:241], v[78:81]
	v_mfma_f32_16x16x32_bf16 v[74:77], v[140:143], v[238:241], v[74:77]
	v_mfma_f32_16x16x32_bf16 v[128:131], v[136:139], v[208:211], v[128:131]
	v_mfma_f32_16x16x32_bf16 v[124:127], v[144:147], v[208:211], v[124:127]
	v_mfma_f32_16x16x32_bf16 v[112:115], v[136:139], v[216:219], v[112:115]
	v_mfma_f32_16x16x32_bf16 v[108:111], v[144:147], v[216:219], v[108:111]
	v_mfma_f32_16x16x32_bf16 v[94:97], v[136:139], v[224:227], v[94:97]
	v_mfma_f32_16x16x32_bf16 v[90:93], v[144:147], v[224:227], v[90:93]
	v_mfma_f32_16x16x32_bf16 v[78:81], v[136:139], v[242:245], v[78:81]
	v_mfma_f32_16x16x32_bf16 v[74:77], v[144:147], v[242:245], v[74:77]
	s_setprio 0
	s_setprio 1
	v_mfma_f32_16x16x32_bf16 v[120:123], v[156:159], v[204:207], v[120:123]
	v_mfma_f32_16x16x32_bf16 v[116:119], v[192:195], v[204:207], v[116:119]
	v_mfma_f32_16x16x32_bf16 v[104:107], v[156:159], v[212:215], v[104:107]
	v_mfma_f32_16x16x32_bf16 v[100:103], v[192:195], v[212:215], v[100:103]
	v_mfma_f32_16x16x32_bf16 v[86:89], v[156:159], v[220:223], v[86:89]
	v_mfma_f32_16x16x32_bf16 v[82:85], v[192:195], v[220:223], v[82:85]
	v_mfma_f32_16x16x32_bf16 v[70:73], v[156:159], v[238:241], v[70:73]
	v_mfma_f32_16x16x32_bf16 v[66:69], v[192:195], v[238:241], v[66:69]
	v_mfma_f32_16x16x32_bf16 v[120:123], v[162:165], v[208:211], v[120:123]
	v_mfma_f32_16x16x32_bf16 v[116:119], v[200:203], v[208:211], v[116:119]
	v_mfma_f32_16x16x32_bf16 v[104:107], v[162:165], v[216:219], v[104:107]
	v_mfma_f32_16x16x32_bf16 v[100:103], v[200:203], v[216:219], v[100:103]
	v_mfma_f32_16x16x32_bf16 v[86:89], v[162:165], v[224:227], v[86:89]
	v_mfma_f32_16x16x32_bf16 v[82:85], v[200:203], v[224:227], v[82:85]
	v_mfma_f32_16x16x32_bf16 v[70:73], v[162:165], v[242:245], v[70:73]
	v_mfma_f32_16x16x32_bf16 v[66:69], v[200:203], v[242:245], v[66:69]
	s_setprio 0
	s_barrier
	s_add_i32 s4, s6, s70
	v_lshl_add_u64 v[166:167], v[166:167], 0, s[42:43]
	s_mov_b32 m0, s4
	ds_read_b128 v[204:207], v191 offset:49152
	ds_read_b128 v[208:211], v191 offset:50176
	ds_read_b128 v[212:215], v191 offset:51200
	ds_read_b128 v[216:219], v191 offset:52224
	ds_read_b128 v[220:223], v191 offset:53248
	ds_read_b128 v[224:227], v191 offset:54272
	ds_read_b128 v[238:241], v191 offset:55296
	ds_read_b128 v[242:245], v191 offset:56320
	global_load_lds_dwordx4 v[166:167], off
	s_add_i32 m0, s4, 0x2000
	s_add_u32 s4, s56, 0x40080
	v_lshl_add_u64 v[166:167], v[170:171], 0, s[42:43]
	s_addc_u32 s5, s57, 0
	s_add_i32 s6, s7, s70
	global_load_lds_dwordx4 v[166:167], off
	v_lshl_add_u64 v[166:167], s[4:5], 0, v[148:149]
	s_mov_b32 m0, s6
	s_nop 0
	global_load_lds_dwordx4 v[166:167], off
	v_lshl_add_u64 v[166:167], s[4:5], 0, v[152:153]
	s_add_i32 m0, s6, 0x2000
	s_nop 0
	global_load_lds_dwordx4 v[166:167], off
	v_lshl_add_u64 v[166:167], v[176:177], 0, s[42:43]
	s_add_i32 m0, s44, 0x8000
	s_nop 0
	global_load_lds_dwordx4 v[166:167], off
	v_lshl_add_u64 v[166:167], v[180:181], 0, s[42:43]
	s_add_i32 m0, s44, 0xa000
	s_nop 0
	global_load_lds_dwordx4 v[166:167], off
	s_waitcnt vmcnt(8)
	s_waitcnt lgkmcnt(0)
	s_barrier
	s_setprio 1
	s_waitcnt lgkmcnt(0)
	v_mfma_f32_16x16x32_bf16 v[62:65], v[132:135], v[204:207], v[62:65]
	v_mfma_f32_16x16x32_bf16 v[58:61], v[140:143], v[204:207], v[58:61]
	v_mfma_f32_16x16x32_bf16 v[46:49], v[132:135], v[212:215], v[46:49]
	v_mfma_f32_16x16x32_bf16 v[42:45], v[140:143], v[212:215], v[42:45]
	v_mfma_f32_16x16x32_bf16 v[30:33], v[132:135], v[220:223], v[30:33]
	v_mfma_f32_16x16x32_bf16 v[26:29], v[140:143], v[220:223], v[26:29]
	v_mfma_f32_16x16x32_bf16 v[14:17], v[132:135], v[238:241], v[14:17]
	v_mfma_f32_16x16x32_bf16 v[10:13], v[140:143], v[238:241], v[10:13]
	v_mfma_f32_16x16x32_bf16 v[62:65], v[136:139], v[208:211], v[62:65]
	v_mfma_f32_16x16x32_bf16 v[58:61], v[144:147], v[208:211], v[58:61]
	v_mfma_f32_16x16x32_bf16 v[46:49], v[136:139], v[216:219], v[46:49]
	v_mfma_f32_16x16x32_bf16 v[42:45], v[144:147], v[216:219], v[42:45]
	v_mfma_f32_16x16x32_bf16 v[30:33], v[136:139], v[224:227], v[30:33]
	v_mfma_f32_16x16x32_bf16 v[26:29], v[144:147], v[224:227], v[26:29]
	v_mfma_f32_16x16x32_bf16 v[14:17], v[136:139], v[242:245], v[14:17]
	v_mfma_f32_16x16x32_bf16 v[10:13], v[144:147], v[242:245], v[10:13]
	s_setprio 0
	s_setprio 1
	v_mfma_f32_16x16x32_bf16 v[54:57], v[156:159], v[204:207], v[54:57]
	v_mfma_f32_16x16x32_bf16 v[50:53], v[192:195], v[204:207], v[50:53]
	v_mfma_f32_16x16x32_bf16 v[38:41], v[156:159], v[212:215], v[38:41]
	v_mfma_f32_16x16x32_bf16 v[34:37], v[192:195], v[212:215], v[34:37]
	v_mfma_f32_16x16x32_bf16 v[22:25], v[156:159], v[220:223], v[22:25]
	v_mfma_f32_16x16x32_bf16 v[18:21], v[192:195], v[220:223], v[18:21]
	v_mfma_f32_16x16x32_bf16 v[6:9], v[156:159], v[238:241], v[6:9]
	v_mfma_f32_16x16x32_bf16 v[2:5], v[192:195], v[238:241], v[2:5]
	v_mfma_f32_16x16x32_bf16 v[54:57], v[162:165], v[208:211], v[54:57]
	v_mfma_f32_16x16x32_bf16 v[50:53], v[200:203], v[208:211], v[50:53]
	v_mfma_f32_16x16x32_bf16 v[38:41], v[162:165], v[216:219], v[38:41]
	v_mfma_f32_16x16x32_bf16 v[34:37], v[200:203], v[216:219], v[34:37]
	v_mfma_f32_16x16x32_bf16 v[22:25], v[162:165], v[224:227], v[22:25]
	v_mfma_f32_16x16x32_bf16 v[18:21], v[200:203], v[224:227], v[18:21]
	v_mfma_f32_16x16x32_bf16 v[6:9], v[162:165], v[242:245], v[6:9]
	v_mfma_f32_16x16x32_bf16 v[2:5], v[200:203], v[242:245], v[2:5]
	s_setprio 0
	s_barrier
	s_mov_b32 s100, 0
	s_add_i32 s92, s92, 2
	s_add_u32 s40, s40, 0x100
	s_addc_u32 s41, s41, 0
	s_add_u32 s90, s90, 0x100
	s_addc_u32 s91, s91, 0
	s_cmp_gt_u32 s92, 13
	s_cbranch_scc0 .LBB0_1011
	s_mov_b32 s100, 1
	s_and_b64 vcc, exec, s[0:1]
	s_cbranch_vccz .LBB0_1014
	s_barrier

.LBB0_1116:
	s_add_u32 s4, s74, 0xfff00080
	s_addc_u32 s5, s75, -1
	s_add_i32 s6, 0, 0x10000
	s_cmp_eq_u32 s95, 60
	s_cselect_b32 vcc_hi, s18, s5
	s_cselect_b32 vcc_lo, s21, s4
	s_cselect_b32 s79, s27, s94
	s_cselect_b32 s78, s69, s71
	s_add_i32 s7, 0, 0x14000
	v_add_u32_e32 v128, s6, v205
	v_add_u32_e32 v160, s7, v205
	ds_read_b128 v[112:115], v128
	ds_read_b128 v[116:119], v128 offset:1024
	ds_read_b128 v[124:127], v128 offset:2048
	ds_read_b128 v[128:131], v128 offset:3072
	ds_read_b128 v[148:151], v160
	ds_read_b128 v[152:155], v160 offset:1024
	ds_read_b128 v[156:159], v160 offset:2048
	ds_read_b128 v[160:163], v160 offset:3072
	s_add_i32 s44, s91, 0
	v_lshl_add_u64 v[194:195], s[74:75], 0, v[98:99]
	s_add_i32 m0, s44, 0xc000
	ds_read_b128 v[164:167], v207
	ds_read_b128 v[168:171], v207 offset:1024
	ds_read_b128 v[178:181], v207 offset:2048
	ds_read_b128 v[182:185], v207 offset:3072
	ds_read_b128 v[186:189], v207 offset:4096
	ds_read_b128 v[190:193], v207 offset:5120
	ds_read_b128 v[200:203], v207 offset:6144
	ds_read_b128 v[208:211], v207 offset:7168
	global_load_lds_dwordx4 v[194:195], off
	v_lshl_add_u64 v[194:195], s[74:75], 0, v[174:175]
	s_add_i32 m0, s44, 0xe000
	s_nop 0
	global_load_lds_dwordx4 v[194:195], off
	s_cmp_eq_u32 s100, 1
	s_cbranch_scc1 .Lmy_sk9
	s_waitcnt vmcnt(8)
.Lmy_sk9:
	s_waitcnt lgkmcnt(0)
	s_barrier
	s_setprio 1
	s_waitcnt lgkmcnt(0)
	v_mfma_f32_16x16x32_bf16 v[144:147], v[112:115], v[164:167], v[144:147]
	v_mfma_f32_16x16x32_bf16 v[140:143], v[124:127], v[164:167], v[140:143]
	v_mfma_f32_16x16x32_bf16 v[120:123], v[112:115], v[178:181], v[120:123]
	v_mfma_f32_16x16x32_bf16 v[108:111], v[124:127], v[178:181], v[108:111]
	v_mfma_f32_16x16x32_bf16 v[94:97], v[112:115], v[186:189], v[94:97]
	v_mfma_f32_16x16x32_bf16 v[90:93], v[124:127], v[186:189], v[90:93]
	v_mfma_f32_16x16x32_bf16 v[78:81], v[112:115], v[200:203], v[78:81]
	v_mfma_f32_16x16x32_bf16 v[74:77], v[124:127], v[200:203], v[74:77]
	v_mfma_f32_16x16x32_bf16 v[144:147], v[116:119], v[168:171], v[144:147]
	v_mfma_f32_16x16x32_bf16 v[140:143], v[128:131], v[168:171], v[140:143]
	v_mfma_f32_16x16x32_bf16 v[120:123], v[116:119], v[182:185], v[120:123]
	v_mfma_f32_16x16x32_bf16 v[108:111], v[128:131], v[182:185], v[108:111]
	v_mfma_f32_16x16x32_bf16 v[94:97], v[116:119], v[190:193], v[94:97]
	v_mfma_f32_16x16x32_bf16 v[90:93], v[128:131], v[190:193], v[90:93]
	v_mfma_f32_16x16x32_bf16 v[78:81], v[116:119], v[208:211], v[78:81]
	v_mfma_f32_16x16x32_bf16 v[74:77], v[128:131], v[208:211], v[74:77]
	s_setprio 0
	s_setprio 1
	v_mfma_f32_16x16x32_bf16 v[136:139], v[148:151], v[164:167], v[136:139]
	v_mfma_f32_16x16x32_bf16 v[132:135], v[156:159], v[164:167], v[132:135]
	v_mfma_f32_16x16x32_bf16 v[104:107], v[148:151], v[178:181], v[104:107]
	v_mfma_f32_16x16x32_bf16 v[100:103], v[156:159], v[178:181], v[100:103]
	v_mfma_f32_16x16x32_bf16 v[86:89], v[148:151], v[186:189], v[86:89]
	v_mfma_f32_16x16x32_bf16 v[82:85], v[156:159], v[186:189], v[82:85]
	v_mfma_f32_16x16x32_bf16 v[70:73], v[148:151], v[200:203], v[70:73]
	v_mfma_f32_16x16x32_bf16 v[66:69], v[156:159], v[200:203], v[66:69]
	v_mfma_f32_16x16x32_bf16 v[136:139], v[152:155], v[168:171], v[136:139]
	v_mfma_f32_16x16x32_bf16 v[132:135], v[160:163], v[168:171], v[132:135]
	v_mfma_f32_16x16x32_bf16 v[104:107], v[152:155], v[182:185], v[104:107]
	v_mfma_f32_16x16x32_bf16 v[100:103], v[160:163], v[182:185], v[100:103]
	v_mfma_f32_16x16x32_bf16 v[86:89], v[152:155], v[190:193], v[86:89]
	v_mfma_f32_16x16x32_bf16 v[82:85], v[160:163], v[190:193], v[82:85]
	v_mfma_f32_16x16x32_bf16 v[70:73], v[152:155], v[208:211], v[70:73]
	v_mfma_f32_16x16x32_bf16 v[66:69], v[160:163], v[208:211], v[66:69]
	s_setprio 0
	s_barrier
	s_add_i32 s4, s6, s91
	v_lshl_add_u64 v[194:195], s[78:79], 0, v[172:173]
	s_mov_b32 m0, s4
	ds_read_b128 v[164:167], v207 offset:16384
	ds_read_b128 v[168:171], v207 offset:17408
	ds_read_b128 v[178:181], v207 offset:18432
	ds_read_b128 v[182:185], v207 offset:19456
	ds_read_b128 v[186:189], v207 offset:20480
	ds_read_b128 v[190:193], v207 offset:21504
	ds_read_b128 v[200:203], v207 offset:22528
	ds_read_b128 v[208:211], v207 offset:23552
	global_load_lds_dwordx4 v[194:195], off
	s_add_i32 m0, s4, 0x2000
	s_add_u32 s4, s78, 0x100000
	v_lshl_add_u64 v[212:213], s[78:79], 0, v[176:177]
	s_addc_u32 s5, s79, 0
	s_add_i32 s6, s7, s91
	global_load_lds_dwordx4 v[212:213], off
	v_lshl_add_u64 v[214:215], s[4:5], 0, v[172:173]
	s_mov_b32 m0, s6
	v_lshl_add_u64 v[216:217], vcc, 0, v[174:175]
	global_load_lds_dwordx4 v[214:215], off
	v_lshl_add_u64 v[214:215], s[4:5], 0, v[176:177]
	s_add_i32 m0, s6, 0x2000
	s_nop 0
	global_load_lds_dwordx4 v[214:215], off
	v_lshl_add_u64 v[214:215], vcc, 0, v[98:99]
	s_mov_b32 m0, s44
	s_nop 0
	global_load_lds_dwordx4 v[214:215], off
	s_add_i32 m0, s44, 0x2000
	s_nop 0
	global_load_lds_dwordx4 v[216:217], off
	s_cmp_eq_u32 s100, 1
	s_cbranch_scc1 .Lmy_sk10
	s_waitcnt vmcnt(8)
.Lmy_sk10:
	s_waitcnt lgkmcnt(0)
	s_barrier
	s_setprio 1
	s_waitcnt lgkmcnt(0)
	v_mfma_f32_16x16x32_bf16 v[62:65], v[112:115], v[164:167], v[62:65]
	v_mfma_f32_16x16x32_bf16 v[58:61], v[124:127], v[164:167], v[58:61]
	v_mfma_f32_16x16x32_bf16 v[46:49], v[112:115], v[178:181], v[46:49]
	v_mfma_f32_16x16x32_bf16 v[42:45], v[124:127], v[178:181], v[42:45]
	v_mfma_f32_16x16x32_bf16 v[30:33], v[112:115], v[186:189], v[30:33]
	v_mfma_f32_16x16x32_bf16 v[26:29], v[124:127], v[186:189], v[26:29]
	v_mfma_f32_16x16x32_bf16 v[14:17], v[112:115], v[200:203], v[14:17]
	v_mfma_f32_16x16x32_bf16 v[10:13], v[124:127], v[200:203], v[10:13]
	v_mfma_f32_16x16x32_bf16 v[62:65], v[116:119], v[168:171], v[62:65]
	v_mfma_f32_16x16x32_bf16 v[58:61], v[128:131], v[168:171], v[58:61]
	v_mfma_f32_16x16x32_bf16 v[46:49], v[116:119], v[182:185], v[46:49]
	v_mfma_f32_16x16x32_bf16 v[42:45], v[128:131], v[182:185], v[42:45]
	v_mfma_f32_16x16x32_bf16 v[30:33], v[116:119], v[190:193], v[30:33]
	v_mfma_f32_16x16x32_bf16 v[26:29], v[128:131], v[190:193], v[26:29]
	v_mfma_f32_16x16x32_bf16 v[14:17], v[116:119], v[208:211], v[14:17]
	v_mfma_f32_16x16x32_bf16 v[10:13], v[128:131], v[208:211], v[10:13]
	s_setprio 0
	s_setprio 1
	v_mfma_f32_16x16x32_bf16 v[54:57], v[148:151], v[164:167], v[54:57]
	v_mfma_f32_16x16x32_bf16 v[50:53], v[156:159], v[164:167], v[50:53]
	v_mfma_f32_16x16x32_bf16 v[38:41], v[148:151], v[178:181], v[38:41]
	v_mfma_f32_16x16x32_bf16 v[34:37], v[156:159], v[178:181], v[34:37]
	v_mfma_f32_16x16x32_bf16 v[22:25], v[148:151], v[186:189], v[22:25]
	v_mfma_f32_16x16x32_bf16 v[18:21], v[156:159], v[186:189], v[18:21]
	v_mfma_f32_16x16x32_bf16 v[6:9], v[148:151], v[200:203], v[6:9]
	v_mfma_f32_16x16x32_bf16 v[2:5], v[156:159], v[200:203], v[2:5]
	v_mfma_f32_16x16x32_bf16 v[54:57], v[152:155], v[168:171], v[54:57]
	v_mfma_f32_16x16x32_bf16 v[50:53], v[160:163], v[168:171], v[50:53]
	v_mfma_f32_16x16x32_bf16 v[38:41], v[152:155], v[182:185], v[38:41]
	v_mfma_f32_16x16x32_bf16 v[34:37], v[160:163], v[182:185], v[34:37]
	v_mfma_f32_16x16x32_bf16 v[22:25], v[152:155], v[190:193], v[22:25]
	v_mfma_f32_16x16x32_bf16 v[18:21], v[160:163], v[190:193], v[18:21]
	v_mfma_f32_16x16x32_bf16 v[6:9], v[152:155], v[208:211], v[6:9]
	v_mfma_f32_16x16x32_bf16 v[2:5], v[160:163], v[208:211], v[2:5]
	s_setprio 0
	s_barrier
	s_add_i32 s6, 0, 0x18000
	s_add_i32 s7, 0, 0x1c000
	v_add_u32_e32 v128, s6, v205
	v_add_u32_e32 v160, s7, v205
	ds_read_b128 v[112:115], v128
	ds_read_b128 v[116:119], v128 offset:1024
	ds_read_b128 v[124:127], v128 offset:2048
	ds_read_b128 v[128:131], v128 offset:3072
	ds_read_b128 v[148:151], v160
	ds_read_b128 v[152:155], v160 offset:1024
	ds_read_b128 v[156:159], v160 offset:2048
	ds_read_b128 v[160:163], v160 offset:3072
	s_add_u32 s4, vcc_lo, 0x100000
	s_addc_u32 s5, vcc_hi, 0
	v_lshl_add_u64 v[218:219], s[4:5], 0, v[98:99]
	s_add_i32 m0, s44, 0x4000
	ds_read_b128 v[164:167], v207 offset:32768
	ds_read_b128 v[168:171], v207 offset:33792
	ds_read_b128 v[178:181], v207 offset:34816
	ds_read_b128 v[182:185], v207 offset:35840
	ds_read_b128 v[186:189], v207 offset:36864
	ds_read_b128 v[190:193], v207 offset:37888
	ds_read_b128 v[200:203], v207 offset:38912
	ds_read_b128 v[208:211], v207 offset:39936
	global_load_lds_dwordx4 v[218:219], off
	v_lshl_add_u64 v[218:219], s[4:5], 0, v[174:175]
	s_add_i32 m0, s44, 0x6000
	s_nop 0
	global_load_lds_dwordx4 v[218:219], off
	s_waitcnt vmcnt(8)
	s_waitcnt lgkmcnt(0)
	s_barrier
	s_setprio 1
	s_waitcnt lgkmcnt(0)
	v_mfma_f32_16x16x32_bf16 v[144:147], v[112:115], v[164:167], v[144:147]
	v_mfma_f32_16x16x32_bf16 v[140:143], v[124:127], v[164:167], v[140:143]
	v_mfma_f32_16x16x32_bf16 v[120:123], v[112:115], v[178:181], v[120:123]
	v_mfma_f32_16x16x32_bf16 v[108:111], v[124:127], v[178:181], v[108:111]
	v_mfma_f32_16x16x32_bf16 v[94:97], v[112:115], v[186:189], v[94:97]
	v_mfma_f32_16x16x32_bf16 v[90:93], v[124:127], v[186:189], v[90:93]
	v_mfma_f32_16x16x32_bf16 v[78:81], v[112:115], v[200:203], v[78:81]
	v_mfma_f32_16x16x32_bf16 v[74:77], v[124:127], v[200:203], v[74:77]
	v_mfma_f32_16x16x32_bf16 v[144:147], v[116:119], v[168:171], v[144:147]
	v_mfma_f32_16x16x32_bf16 v[140:143], v[128:131], v[168:171], v[140:143]
	v_mfma_f32_16x16x32_bf16 v[120:123], v[116:119], v[182:185], v[120:123]
	v_mfma_f32_16x16x32_bf16 v[108:111], v[128:131], v[182:185], v[108:111]
	v_mfma_f32_16x16x32_bf16 v[94:97], v[116:119], v[190:193], v[94:97]
	v_mfma_f32_16x16x32_bf16 v[90:93], v[128:131], v[190:193], v[90:93]
	v_mfma_f32_16x16x32_bf16 v[78:81], v[116:119], v[208:211], v[78:81]
	v_mfma_f32_16x16x32_bf16 v[74:77], v[128:131], v[208:211], v[74:77]
	s_setprio 0
	s_setprio 1
	v_mfma_f32_16x16x32_bf16 v[136:139], v[148:151], v[164:167], v[136:139]
	v_mfma_f32_16x16x32_bf16 v[132:135], v[156:159], v[164:167], v[132:135]
	v_mfma_f32_16x16x32_bf16 v[104:107], v[148:151], v[178:181], v[104:107]
	v_mfma_f32_16x16x32_bf16 v[100:103], v[156:159], v[178:181], v[100:103]
	v_mfma_f32_16x16x32_bf16 v[86:89], v[148:151], v[186:189], v[86:89]
	v_mfma_f32_16x16x32_bf16 v[82:85], v[156:159], v[186:189], v[82:85]
	v_mfma_f32_16x16x32_bf16 v[70:73], v[148:151], v[200:203], v[70:73]
	v_mfma_f32_16x16x32_bf16 v[66:69], v[156:159], v[200:203], v[66:69]
	v_mfma_f32_16x16x32_bf16 v[136:139], v[152:155], v[168:171], v[136:139]
	v_mfma_f32_16x16x32_bf16 v[132:135], v[160:163], v[168:171], v[132:135]
	v_mfma_f32_16x16x32_bf16 v[104:107], v[152:155], v[182:185], v[104:107]
	v_mfma_f32_16x16x32_bf16 v[100:103], v[160:163], v[182:185], v[100:103]
	v_mfma_f32_16x16x32_bf16 v[86:89], v[152:155], v[190:193], v[86:89]
	v_mfma_f32_16x16x32_bf16 v[82:85], v[160:163], v[190:193], v[82:85]
	v_mfma_f32_16x16x32_bf16 v[70:73], v[152:155], v[208:211], v[70:73]
	v_mfma_f32_16x16x32_bf16 v[66:69], v[160:163], v[208:211], v[66:69]
	s_setprio 0
	s_barrier
	s_add_i32 s4, s6, s91
	v_lshl_add_u64 v[194:195], v[194:195], 0, s[42:43]
	s_mov_b32 m0, s4
	ds_read_b128 v[164:167], v207 offset:49152
	ds_read_b128 v[168:171], v207 offset:50176
	ds_read_b128 v[178:181], v207 offset:51200
	ds_read_b128 v[182:185], v207 offset:52224
	ds_read_b128 v[186:189], v207 offset:53248
	ds_read_b128 v[190:193], v207 offset:54272
	ds_read_b128 v[200:203], v207 offset:55296
	ds_read_b128 v[208:211], v207 offset:56320
	global_load_lds_dwordx4 v[194:195], off
	s_add_i32 m0, s4, 0x2000
	s_add_u32 s4, s78, 0x100080
	v_lshl_add_u64 v[194:195], v[212:213], 0, s[42:43]
	s_addc_u32 s5, s79, 0
	s_add_i32 s6, s7, s91
	global_load_lds_dwordx4 v[194:195], off
	v_lshl_add_u64 v[194:195], s[4:5], 0, v[172:173]
	s_mov_b32 m0, s6
	s_nop 0
	global_load_lds_dwordx4 v[194:195], off
	v_lshl_add_u64 v[194:195], s[4:5], 0, v[176:177]
	s_add_i32 m0, s6, 0x2000
	s_nop 0
	global_load_lds_dwordx4 v[194:195], off
	v_lshl_add_u64 v[194:195], v[214:215], 0, s[42:43]
	s_add_i32 m0, s44, 0x8000
	s_nop 0
	global_load_lds_dwordx4 v[194:195], off
	v_lshl_add_u64 v[194:195], v[216:217], 0, s[42:43]
	s_add_i32 m0, s44, 0xa000
	s_nop 0
	global_load_lds_dwordx4 v[194:195], off
	s_waitcnt vmcnt(8)
	s_waitcnt lgkmcnt(0)
	s_barrier
	s_setprio 1
	s_waitcnt lgkmcnt(0)
	v_mfma_f32_16x16x32_bf16 v[62:65], v[112:115], v[164:167], v[62:65]
	v_mfma_f32_16x16x32_bf16 v[58:61], v[124:127], v[164:167], v[58:61]
	v_mfma_f32_16x16x32_bf16 v[46:49], v[112:115], v[178:181], v[46:49]
	v_mfma_f32_16x16x32_bf16 v[42:45], v[124:127], v[178:181], v[42:45]
	v_mfma_f32_16x16x32_bf16 v[30:33], v[112:115], v[186:189], v[30:33]
	v_mfma_f32_16x16x32_bf16 v[26:29], v[124:127], v[186:189], v[26:29]
	v_mfma_f32_16x16x32_bf16 v[14:17], v[112:115], v[200:203], v[14:17]
	v_mfma_f32_16x16x32_bf16 v[10:13], v[124:127], v[200:203], v[10:13]
	v_mfma_f32_16x16x32_bf16 v[62:65], v[116:119], v[168:171], v[62:65]
	v_mfma_f32_16x16x32_bf16 v[58:61], v[128:131], v[168:171], v[58:61]
	v_mfma_f32_16x16x32_bf16 v[46:49], v[116:119], v[182:185], v[46:49]
	v_mfma_f32_16x16x32_bf16 v[42:45], v[128:131], v[182:185], v[42:45]
	v_mfma_f32_16x16x32_bf16 v[30:33], v[116:119], v[190:193], v[30:33]
	v_mfma_f32_16x16x32_bf16 v[26:29], v[128:131], v[190:193], v[26:29]
	v_mfma_f32_16x16x32_bf16 v[14:17], v[116:119], v[208:211], v[14:17]
	v_mfma_f32_16x16x32_bf16 v[10:13], v[128:131], v[208:211], v[10:13]
	s_setprio 0
	s_setprio 1
	v_mfma_f32_16x16x32_bf16 v[54:57], v[148:151], v[164:167], v[54:57]
	v_mfma_f32_16x16x32_bf16 v[50:53], v[156:159], v[164:167], v[50:53]
	v_mfma_f32_16x16x32_bf16 v[38:41], v[148:151], v[178:181], v[38:41]
	v_mfma_f32_16x16x32_bf16 v[34:37], v[156:159], v[178:181], v[34:37]
	v_mfma_f32_16x16x32_bf16 v[22:25], v[148:151], v[186:189], v[22:25]
	v_mfma_f32_16x16x32_bf16 v[18:21], v[156:159], v[186:189], v[18:21]
	v_mfma_f32_16x16x32_bf16 v[6:9], v[148:151], v[200:203], v[6:9]
	v_mfma_f32_16x16x32_bf16 v[2:5], v[156:159], v[200:203], v[2:5]
	v_mfma_f32_16x16x32_bf16 v[54:57], v[152:155], v[168:171], v[54:57]
	v_mfma_f32_16x16x32_bf16 v[50:53], v[160:163], v[168:171], v[50:53]
	v_mfma_f32_16x16x32_bf16 v[38:41], v[152:155], v[182:185], v[38:41]
	v_mfma_f32_16x16x32_bf16 v[34:37], v[160:163], v[182:185], v[34:37]
	v_mfma_f32_16x16x32_bf16 v[22:25], v[152:155], v[190:193], v[22:25]
	v_mfma_f32_16x16x32_bf16 v[18:21], v[160:163], v[190:193], v[18:21]
	v_mfma_f32_16x16x32_bf16 v[6:9], v[152:155], v[208:211], v[6:9]
	v_mfma_f32_16x16x32_bf16 v[2:5], v[160:163], v[208:211], v[2:5]
	s_setprio 0
	s_barrier
	s_mov_b32 s100, 0
	s_add_i32 s95, s95, 2
	s_add_u32 s74, s74, 0x100
	s_addc_u32 s75, s75, 0
	s_add_u32 s71, s71, 0x100
	s_addc_u32 s94, s94, 0
	s_cmp_gt_u32 s95, 61
	s_cbranch_scc0 .LBB0_1116
	s_mov_b32 s100, 1
	s_and_b64 vcc, exec, s[10:11]
	s_cbranch_vccz .LBB0_1119
	s_barrier

.LBB0_1172:
	s_add_u32 s4, s70, 0xfff00080
	s_addc_u32 s5, s71, -1
	s_add_i32 s6, 0, 0x10000
	s_cmp_eq_u32 s95, 60
	s_cselect_b32 s79, s18, s5
	s_cselect_b32 s78, s27, s4
	s_cselect_b32 s75, s15, s94
	s_cselect_b32 s74, s57, s69
	s_add_i32 s7, 0, 0x14000
	v_add_u32_e32 v104, s6, v239
	v_add_u32_e32 v128, s7, v239
	ds_read_b128 v[90:93], v104
	ds_read_b128 v[94:97], v104 offset:1024
	ds_read_b128 v[100:103], v104 offset:2048
	ds_read_b128 v[104:107], v104 offset:3072
	ds_read_b128 v[108:111], v128
	ds_read_b128 v[112:115], v128 offset:1024
	ds_read_b128 v[120:123], v128 offset:2048
	ds_read_b128 v[128:131], v128 offset:3072
	s_add_i32 s44, s91, 0
	v_lshl_add_u64 v[200:201], s[70:71], 0, v[98:99]
	s_add_i32 m0, s44, 0xc000
	ds_read_b128 v[164:167], v241
	ds_read_b128 v[168:171], v241 offset:1024
	ds_read_b128 v[172:175], v241 offset:2048
	ds_read_b128 v[176:179], v241 offset:3072
	ds_read_b128 v[180:183], v241 offset:4096
	ds_read_b128 v[184:187], v241 offset:5120
	ds_read_b128 v[188:191], v241 offset:6144
	ds_read_b128 v[192:195], v241 offset:7168
	global_load_lds_dwordx4 v[200:201], off
	v_lshl_add_u64 v[200:201], s[70:71], 0, v[206:207]
	s_add_i32 m0, s44, 0xe000
	s_nop 0
	global_load_lds_dwordx4 v[200:201], off
	s_cmp_eq_u32 s100, 1
	s_cbranch_scc1 .Lmy_sk11
	s_waitcnt vmcnt(8)
.Lmy_sk11:
	s_waitcnt lgkmcnt(0)
	s_barrier
	s_setprio 1
	s_waitcnt lgkmcnt(0)
	v_mfma_f32_16x16x32_bf16 v[160:163], v[90:93], v[164:167], v[160:163]
	v_mfma_f32_16x16x32_bf16 v[156:159], v[100:103], v[164:167], v[156:159]
	v_mfma_f32_16x16x32_bf16 v[144:147], v[90:93], v[172:175], v[144:147]
	v_mfma_f32_16x16x32_bf16 v[140:143], v[100:103], v[172:175], v[140:143]
	v_mfma_f32_16x16x32_bf16 v[124:127], v[90:93], v[180:183], v[124:127]
	v_mfma_f32_16x16x32_bf16 v[116:119], v[100:103], v[180:183], v[116:119]
	v_mfma_f32_16x16x32_bf16 v[78:81], v[90:93], v[188:191], v[78:81]
	v_mfma_f32_16x16x32_bf16 v[74:77], v[100:103], v[188:191], v[74:77]
	v_mfma_f32_16x16x32_bf16 v[160:163], v[94:97], v[168:171], v[160:163]
	v_mfma_f32_16x16x32_bf16 v[156:159], v[104:107], v[168:171], v[156:159]
	v_mfma_f32_16x16x32_bf16 v[144:147], v[94:97], v[176:179], v[144:147]
	v_mfma_f32_16x16x32_bf16 v[140:143], v[104:107], v[176:179], v[140:143]
	v_mfma_f32_16x16x32_bf16 v[124:127], v[94:97], v[184:187], v[124:127]
	v_mfma_f32_16x16x32_bf16 v[116:119], v[104:107], v[184:187], v[116:119]
	v_mfma_f32_16x16x32_bf16 v[78:81], v[94:97], v[192:195], v[78:81]
	v_mfma_f32_16x16x32_bf16 v[74:77], v[104:107], v[192:195], v[74:77]
	s_setprio 0
	s_setprio 1
	v_mfma_f32_16x16x32_bf16 v[152:155], v[108:111], v[164:167], v[152:155]
	v_mfma_f32_16x16x32_bf16 v[148:151], v[120:123], v[164:167], v[148:151]
	v_mfma_f32_16x16x32_bf16 v[136:139], v[108:111], v[172:175], v[136:139]
	v_mfma_f32_16x16x32_bf16 v[132:135], v[120:123], v[172:175], v[132:135]
	v_mfma_f32_16x16x32_bf16 v[86:89], v[108:111], v[180:183], v[86:89]
	v_mfma_f32_16x16x32_bf16 v[82:85], v[120:123], v[180:183], v[82:85]
	v_mfma_f32_16x16x32_bf16 v[70:73], v[108:111], v[188:191], v[70:73]
	v_mfma_f32_16x16x32_bf16 v[66:69], v[120:123], v[188:191], v[66:69]
	v_mfma_f32_16x16x32_bf16 v[152:155], v[112:115], v[168:171], v[152:155]
	v_mfma_f32_16x16x32_bf16 v[148:151], v[128:131], v[168:171], v[148:151]
	v_mfma_f32_16x16x32_bf16 v[136:139], v[112:115], v[176:179], v[136:139]
	v_mfma_f32_16x16x32_bf16 v[132:135], v[128:131], v[176:179], v[132:135]
	v_mfma_f32_16x16x32_bf16 v[86:89], v[112:115], v[184:187], v[86:89]
	v_mfma_f32_16x16x32_bf16 v[82:85], v[128:131], v[184:187], v[82:85]
	v_mfma_f32_16x16x32_bf16 v[70:73], v[112:115], v[192:195], v[70:73]
	v_mfma_f32_16x16x32_bf16 v[66:69], v[128:131], v[192:195], v[66:69]
	s_setprio 0
	s_barrier
	s_add_i32 s4, s6, s91
	v_lshl_add_u64 v[200:201], s[74:75], 0, v[204:205]
	s_mov_b32 m0, s4
	ds_read_b128 v[164:167], v241 offset:16384
	ds_read_b128 v[168:171], v241 offset:17408
	ds_read_b128 v[172:175], v241 offset:18432
	ds_read_b128 v[176:179], v241 offset:19456
	ds_read_b128 v[180:183], v241 offset:20480
	ds_read_b128 v[184:187], v241 offset:21504
	ds_read_b128 v[188:191], v241 offset:22528
	ds_read_b128 v[192:195], v241 offset:23552
	global_load_lds_dwordx4 v[200:201], off
	s_add_i32 m0, s4, 0x2000
	s_add_u32 s4, s74, 0x100000
	v_lshl_add_u64 v[202:203], s[74:75], 0, v[208:209]
	s_addc_u32 s5, s75, 0
	s_add_i32 s6, s7, s91
	global_load_lds_dwordx4 v[202:203], off
	v_lshl_add_u64 v[210:211], s[4:5], 0, v[204:205]
	s_mov_b32 m0, s6
	v_lshl_add_u64 v[212:213], s[78:79], 0, v[206:207]
	global_load_lds_dwordx4 v[210:211], off
	v_lshl_add_u64 v[210:211], s[4:5], 0, v[208:209]
	s_add_i32 m0, s6, 0x2000
	s_nop 0
	global_load_lds_dwordx4 v[210:211], off
	v_lshl_add_u64 v[210:211], s[78:79], 0, v[98:99]
	s_mov_b32 m0, s44
	s_nop 0
	global_load_lds_dwordx4 v[210:211], off
	s_add_i32 m0, s44, 0x2000
	s_nop 0
	global_load_lds_dwordx4 v[212:213], off
	s_cmp_eq_u32 s100, 1
	s_cbranch_scc1 .Lmy_sk12
	s_waitcnt vmcnt(8)
.Lmy_sk12:
	s_waitcnt lgkmcnt(0)
	s_barrier
	s_setprio 1
	s_waitcnt lgkmcnt(0)
	v_mfma_f32_16x16x32_bf16 v[62:65], v[90:93], v[164:167], v[62:65]
	v_mfma_f32_16x16x32_bf16 v[58:61], v[100:103], v[164:167], v[58:61]
	v_mfma_f32_16x16x32_bf16 v[46:49], v[90:93], v[172:175], v[46:49]
	v_mfma_f32_16x16x32_bf16 v[42:45], v[100:103], v[172:175], v[42:45]
	v_mfma_f32_16x16x32_bf16 v[30:33], v[90:93], v[180:183], v[30:33]
	v_mfma_f32_16x16x32_bf16 v[26:29], v[100:103], v[180:183], v[26:29]
	v_mfma_f32_16x16x32_bf16 v[14:17], v[90:93], v[188:191], v[14:17]
	v_mfma_f32_16x16x32_bf16 v[10:13], v[100:103], v[188:191], v[10:13]
	v_mfma_f32_16x16x32_bf16 v[62:65], v[94:97], v[168:171], v[62:65]
	v_mfma_f32_16x16x32_bf16 v[58:61], v[104:107], v[168:171], v[58:61]
	v_mfma_f32_16x16x32_bf16 v[46:49], v[94:97], v[176:179], v[46:49]
	v_mfma_f32_16x16x32_bf16 v[42:45], v[104:107], v[176:179], v[42:45]
	v_mfma_f32_16x16x32_bf16 v[30:33], v[94:97], v[184:187], v[30:33]
	v_mfma_f32_16x16x32_bf16 v[26:29], v[104:107], v[184:187], v[26:29]
	v_mfma_f32_16x16x32_bf16 v[14:17], v[94:97], v[192:195], v[14:17]
	v_mfma_f32_16x16x32_bf16 v[10:13], v[104:107], v[192:195], v[10:13]
	s_setprio 0
	s_setprio 1
	v_mfma_f32_16x16x32_bf16 v[54:57], v[108:111], v[164:167], v[54:57]
	v_mfma_f32_16x16x32_bf16 v[50:53], v[120:123], v[164:167], v[50:53]
	v_mfma_f32_16x16x32_bf16 v[38:41], v[108:111], v[172:175], v[38:41]
	v_mfma_f32_16x16x32_bf16 v[34:37], v[120:123], v[172:175], v[34:37]
	v_mfma_f32_16x16x32_bf16 v[22:25], v[108:111], v[180:183], v[22:25]
	v_mfma_f32_16x16x32_bf16 v[18:21], v[120:123], v[180:183], v[18:21]
	v_mfma_f32_16x16x32_bf16 v[6:9], v[108:111], v[188:191], v[6:9]
	v_mfma_f32_16x16x32_bf16 v[2:5], v[120:123], v[188:191], v[2:5]
	v_mfma_f32_16x16x32_bf16 v[54:57], v[112:115], v[168:171], v[54:57]
	v_mfma_f32_16x16x32_bf16 v[50:53], v[128:131], v[168:171], v[50:53]
	v_mfma_f32_16x16x32_bf16 v[38:41], v[112:115], v[176:179], v[38:41]
	v_mfma_f32_16x16x32_bf16 v[34:37], v[128:131], v[176:179], v[34:37]
	v_mfma_f32_16x16x32_bf16 v[22:25], v[112:115], v[184:187], v[22:25]
	v_mfma_f32_16x16x32_bf16 v[18:21], v[128:131], v[184:187], v[18:21]
	v_mfma_f32_16x16x32_bf16 v[6:9], v[112:115], v[192:195], v[6:9]
	v_mfma_f32_16x16x32_bf16 v[2:5], v[128:131], v[192:195], v[2:5]
	s_setprio 0
	s_barrier
	s_add_i32 s6, 0, 0x18000
	s_add_i32 s7, 0, 0x1c000
	v_add_u32_e32 v104, s6, v239
	v_add_u32_e32 v128, s7, v239
	ds_read_b128 v[90:93], v104
	ds_read_b128 v[94:97], v104 offset:1024
	ds_read_b128 v[100:103], v104 offset:2048
	ds_read_b128 v[104:107], v104 offset:3072
	ds_read_b128 v[108:111], v128
	ds_read_b128 v[112:115], v128 offset:1024
	ds_read_b128 v[120:123], v128 offset:2048
	ds_read_b128 v[128:131], v128 offset:3072
	s_add_u32 s4, s78, 0x100000
	s_addc_u32 s5, s79, 0
	v_lshl_add_u64 v[214:215], s[4:5], 0, v[98:99]
	s_add_i32 m0, s44, 0x4000
	ds_read_b128 v[164:167], v241 offset:32768
	ds_read_b128 v[168:171], v241 offset:33792
	ds_read_b128 v[172:175], v241 offset:34816
	ds_read_b128 v[176:179], v241 offset:35840
	ds_read_b128 v[180:183], v241 offset:36864
	ds_read_b128 v[184:187], v241 offset:37888
	ds_read_b128 v[188:191], v241 offset:38912
	ds_read_b128 v[192:195], v241 offset:39936
	global_load_lds_dwordx4 v[214:215], off
	v_lshl_add_u64 v[214:215], s[4:5], 0, v[206:207]
	s_add_i32 m0, s44, 0x6000
	s_nop 0
	global_load_lds_dwordx4 v[214:215], off
	s_waitcnt vmcnt(8)
	s_waitcnt lgkmcnt(0)
	s_barrier
	s_setprio 1
	s_waitcnt lgkmcnt(0)
	v_mfma_f32_16x16x32_bf16 v[160:163], v[90:93], v[164:167], v[160:163]
	v_mfma_f32_16x16x32_bf16 v[156:159], v[100:103], v[164:167], v[156:159]
	v_mfma_f32_16x16x32_bf16 v[144:147], v[90:93], v[172:175], v[144:147]
	v_mfma_f32_16x16x32_bf16 v[140:143], v[100:103], v[172:175], v[140:143]
	v_mfma_f32_16x16x32_bf16 v[124:127], v[90:93], v[180:183], v[124:127]
	v_mfma_f32_16x16x32_bf16 v[116:119], v[100:103], v[180:183], v[116:119]
	v_mfma_f32_16x16x32_bf16 v[78:81], v[90:93], v[188:191], v[78:81]
	v_mfma_f32_16x16x32_bf16 v[74:77], v[100:103], v[188:191], v[74:77]
	v_mfma_f32_16x16x32_bf16 v[160:163], v[94:97], v[168:171], v[160:163]
	v_mfma_f32_16x16x32_bf16 v[156:159], v[104:107], v[168:171], v[156:159]
	v_mfma_f32_16x16x32_bf16 v[144:147], v[94:97], v[176:179], v[144:147]
	v_mfma_f32_16x16x32_bf16 v[140:143], v[104:107], v[176:179], v[140:143]
	v_mfma_f32_16x16x32_bf16 v[124:127], v[94:97], v[184:187], v[124:127]
	v_mfma_f32_16x16x32_bf16 v[116:119], v[104:107], v[184:187], v[116:119]
	v_mfma_f32_16x16x32_bf16 v[78:81], v[94:97], v[192:195], v[78:81]
	v_mfma_f32_16x16x32_bf16 v[74:77], v[104:107], v[192:195], v[74:77]
	s_setprio 0
	s_setprio 1
	v_mfma_f32_16x16x32_bf16 v[152:155], v[108:111], v[164:167], v[152:155]
	v_mfma_f32_16x16x32_bf16 v[148:151], v[120:123], v[164:167], v[148:151]
	v_mfma_f32_16x16x32_bf16 v[136:139], v[108:111], v[172:175], v[136:139]
	v_mfma_f32_16x16x32_bf16 v[132:135], v[120:123], v[172:175], v[132:135]
	v_mfma_f32_16x16x32_bf16 v[86:89], v[108:111], v[180:183], v[86:89]
	v_mfma_f32_16x16x32_bf16 v[82:85], v[120:123], v[180:183], v[82:85]
	v_mfma_f32_16x16x32_bf16 v[70:73], v[108:111], v[188:191], v[70:73]
	v_mfma_f32_16x16x32_bf16 v[66:69], v[120:123], v[188:191], v[66:69]
	v_mfma_f32_16x16x32_bf16 v[152:155], v[112:115], v[168:171], v[152:155]
	v_mfma_f32_16x16x32_bf16 v[148:151], v[128:131], v[168:171], v[148:151]
	v_mfma_f32_16x16x32_bf16 v[136:139], v[112:115], v[176:179], v[136:139]
	v_mfma_f32_16x16x32_bf16 v[132:135], v[128:131], v[176:179], v[132:135]
	v_mfma_f32_16x16x32_bf16 v[86:89], v[112:115], v[184:187], v[86:89]
	v_mfma_f32_16x16x32_bf16 v[82:85], v[128:131], v[184:187], v[82:85]
	v_mfma_f32_16x16x32_bf16 v[70:73], v[112:115], v[192:195], v[70:73]
	v_mfma_f32_16x16x32_bf16 v[66:69], v[128:131], v[192:195], v[66:69]
	s_setprio 0
	s_barrier
	s_add_i32 s4, s6, s91
	v_lshl_add_u64 v[200:201], v[200:201], 0, s[42:43]
	s_mov_b32 m0, s4
	ds_read_b128 v[164:167], v241 offset:49152
	ds_read_b128 v[168:171], v241 offset:50176
	ds_read_b128 v[172:175], v241 offset:51200
	ds_read_b128 v[176:179], v241 offset:52224
	ds_read_b128 v[180:183], v241 offset:53248
	ds_read_b128 v[184:187], v241 offset:54272
	ds_read_b128 v[188:191], v241 offset:55296
	ds_read_b128 v[192:195], v241 offset:56320
	global_load_lds_dwordx4 v[200:201], off
	s_add_i32 m0, s4, 0x2000
	s_add_u32 s4, s74, 0x100080
	v_lshl_add_u64 v[200:201], v[202:203], 0, s[42:43]
	s_addc_u32 s5, s75, 0
	s_add_i32 s6, s7, s91
	global_load_lds_dwordx4 v[200:201], off
	v_lshl_add_u64 v[200:201], s[4:5], 0, v[204:205]
	s_mov_b32 m0, s6
	s_nop 0
	global_load_lds_dwordx4 v[200:201], off
	v_lshl_add_u64 v[200:201], s[4:5], 0, v[208:209]
	s_add_i32 m0, s6, 0x2000
	s_nop 0
	global_load_lds_dwordx4 v[200:201], off
	v_lshl_add_u64 v[200:201], v[210:211], 0, s[42:43]
	s_add_i32 m0, s44, 0x8000
	s_nop 0
	global_load_lds_dwordx4 v[200:201], off
	v_lshl_add_u64 v[200:201], v[212:213], 0, s[42:43]
	s_add_i32 m0, s44, 0xa000
	s_nop 0
	global_load_lds_dwordx4 v[200:201], off
	s_waitcnt vmcnt(8)
	s_waitcnt lgkmcnt(0)
	s_barrier
	s_setprio 1
	s_waitcnt lgkmcnt(0)
	v_mfma_f32_16x16x32_bf16 v[62:65], v[90:93], v[164:167], v[62:65]
	v_mfma_f32_16x16x32_bf16 v[58:61], v[100:103], v[164:167], v[58:61]
	v_mfma_f32_16x16x32_bf16 v[46:49], v[90:93], v[172:175], v[46:49]
	v_mfma_f32_16x16x32_bf16 v[42:45], v[100:103], v[172:175], v[42:45]
	v_mfma_f32_16x16x32_bf16 v[30:33], v[90:93], v[180:183], v[30:33]
	v_mfma_f32_16x16x32_bf16 v[26:29], v[100:103], v[180:183], v[26:29]
	v_mfma_f32_16x16x32_bf16 v[14:17], v[90:93], v[188:191], v[14:17]
	v_mfma_f32_16x16x32_bf16 v[10:13], v[100:103], v[188:191], v[10:13]
	v_mfma_f32_16x16x32_bf16 v[62:65], v[94:97], v[168:171], v[62:65]
	v_mfma_f32_16x16x32_bf16 v[58:61], v[104:107], v[168:171], v[58:61]
	v_mfma_f32_16x16x32_bf16 v[46:49], v[94:97], v[176:179], v[46:49]
	v_mfma_f32_16x16x32_bf16 v[42:45], v[104:107], v[176:179], v[42:45]
	v_mfma_f32_16x16x32_bf16 v[30:33], v[94:97], v[184:187], v[30:33]
	v_mfma_f32_16x16x32_bf16 v[26:29], v[104:107], v[184:187], v[26:29]
	v_mfma_f32_16x16x32_bf16 v[14:17], v[94:97], v[192:195], v[14:17]
	v_mfma_f32_16x16x32_bf16 v[10:13], v[104:107], v[192:195], v[10:13]
	s_setprio 0
	s_setprio 1
	v_mfma_f32_16x16x32_bf16 v[54:57], v[108:111], v[164:167], v[54:57]
	v_mfma_f32_16x16x32_bf16 v[50:53], v[120:123], v[164:167], v[50:53]
	v_mfma_f32_16x16x32_bf16 v[38:41], v[108:111], v[172:175], v[38:41]
	v_mfma_f32_16x16x32_bf16 v[34:37], v[120:123], v[172:175], v[34:37]
	v_mfma_f32_16x16x32_bf16 v[22:25], v[108:111], v[180:183], v[22:25]
	v_mfma_f32_16x16x32_bf16 v[18:21], v[120:123], v[180:183], v[18:21]
	v_mfma_f32_16x16x32_bf16 v[6:9], v[108:111], v[188:191], v[6:9]
	v_mfma_f32_16x16x32_bf16 v[2:5], v[120:123], v[188:191], v[2:5]
	v_mfma_f32_16x16x32_bf16 v[54:57], v[112:115], v[168:171], v[54:57]
	v_mfma_f32_16x16x32_bf16 v[50:53], v[128:131], v[168:171], v[50:53]
	v_mfma_f32_16x16x32_bf16 v[38:41], v[112:115], v[176:179], v[38:41]
	v_mfma_f32_16x16x32_bf16 v[34:37], v[128:131], v[176:179], v[34:37]
	v_mfma_f32_16x16x32_bf16 v[22:25], v[112:115], v[184:187], v[22:25]
	v_mfma_f32_16x16x32_bf16 v[18:21], v[128:131], v[184:187], v[18:21]
	v_mfma_f32_16x16x32_bf16 v[6:9], v[112:115], v[192:195], v[6:9]
	v_mfma_f32_16x16x32_bf16 v[2:5], v[128:131], v[192:195], v[2:5]
	s_setprio 0
	s_barrier
	s_mov_b32 s100, 0
	s_add_i32 s95, s95, 2
	s_add_u32 s70, s70, 0x100
	s_addc_u32 s71, s71, 0
	s_add_u32 s69, s69, 0x100
	s_addc_u32 s94, s94, 0
	s_cmp_gt_u32 s95, 61
	s_cbranch_scc0 .LBB0_1172
	s_mov_b32 s100, 1
	s_and_b64 vcc, exec, s[10:11]
	s_cbranch_vccz .LBB0_1175
	s_barrier

.LBB0_1301:
	s_or_b64 exec, exec, s[12:13]
	s_waitcnt lgkmcnt(0)
	s_barrier
	s_mov_b32 s100, 0
	s_mov_b64 s[12:13], -1
	s_and_b64 vcc, exec, s[10:11]
	s_cbranch_vccnz .LBB0_1211
	s_branch .LBB0_1310

.LBB0_1309:
	s_or_b64 exec, exec, s[0:1]
	s_waitcnt vmcnt(0) lgkmcnt(0)
	s_barrier
	s_mov_b32 s100, 0
	s_mov_b64 s[12:13], -1

	.amdhsa_kernel _Z6mk_fwd4Args
		.amdhsa_group_segment_fixed_size 0
		.amdhsa_private_segment_fixed_size 0
		.amdhsa_kernarg_size 448
		.amdhsa_user_sgpr_count 2
		.amdhsa_user_sgpr_dispatch_ptr 0
		.amdhsa_user_sgpr_queue_ptr 0
		.amdhsa_user_sgpr_kernarg_segment_ptr 1
		.amdhsa_user_sgpr_dispatch_id 0
		.amdhsa_user_sgpr_kernarg_preload_length 0
		.amdhsa_user_sgpr_kernarg_preload_offset 0
		.amdhsa_user_sgpr_private_segment_size 0
		.amdhsa_uses_dynamic_stack 0
		.amdhsa_enable_private_segment 0
		.amdhsa_system_sgpr_workgroup_id_x 1
		.amdhsa_system_sgpr_workgroup_id_y 0
		.amdhsa_system_sgpr_workgroup_id_z 0
		.amdhsa_system_sgpr_workgroup_info 0
		.amdhsa_system_vgpr_workitem_id 0
		.amdhsa_next_free_vgpr 256
		.amdhsa_next_free_sgpr 102
		.amdhsa_accum_offset 256
		.amdhsa_reserve_vcc 1
		.amdhsa_float_round_mode_32 0
		.amdhsa_float_round_mode_16_64 0
		.amdhsa_float_denorm_mode_32 3
		.amdhsa_float_denorm_mode_16_64 3
		.amdhsa_dx10_clamp 1
		.amdhsa_ieee_mode 1
		.amdhsa_fp16_overflow 0
		.amdhsa_tg_split 0
		.amdhsa_exception_fp_ieee_invalid_op 0
		.amdhsa_exception_fp_denorm_src 0
		.amdhsa_exception_fp_ieee_div_zero 0
		.amdhsa_exception_fp_ieee_overflow 0
		.amdhsa_exception_fp_ieee_underflow 0
		.amdhsa_exception_fp_ieee_inexact 0
		.amdhsa_exception_int_div_zero 0
	.end_amdhsa_kernel

.Lfunc_end0:
	.size	_Z6mk_fwd4Args, .Lfunc_end0-_Z6mk_fwd4Args
	.set _Z6mk_fwd4Args.num_vgpr, 256
	.set _Z6mk_fwd4Args.num_agpr, 0
	.set _Z6mk_fwd4Args.numbered_sgpr, 102
	.set _Z6mk_fwd4Args.num_named_barrier, 0
	.set _Z6mk_fwd4Args.private_seg_size, 0
	.set _Z6mk_fwd4Args.uses_vcc, 1
	.set _Z6mk_fwd4Args.uses_flat_scratch, 0
	.set _Z6mk_fwd4Args.has_dyn_sized_stack, 0
	.set _Z6mk_fwd4Args.has_recursion, 0
	.set _Z6mk_fwd4Args.has_indirect_call, 0

amdhsa.kernels:
  - .agpr_count:     0
    .args:
      - .offset:         0
        .size:           192
        .value_kind:     by_value
      - .offset:         192
        .size:           4
        .value_kind:     hidden_block_count_x
      - .offset:         196
        .size:           4
        .value_kind:     hidden_block_count_y
      - .offset:         200
        .size:           4
        .value_kind:     hidden_block_count_z
      - .offset:         204
        .size:           2
        .value_kind:     hidden_group_size_x
      - .offset:         206
        .size:           2
        .value_kind:     hidden_group_size_y
      - .offset:         208
        .size:           2
        .value_kind:     hidden_group_size_z
      - .offset:         210
        .size:           2
        .value_kind:     hidden_remainder_x
      - .offset:         212
        .size:           2
        .value_kind:     hidden_remainder_y
      - .offset:         214
        .size:           2
        .value_kind:     hidden_remainder_z
      - .offset:         232
        .size:           8
        .value_kind:     hidden_global_offset_x
      - .offset:         240
        .size:           8
        .value_kind:     hidden_global_offset_y
      - .offset:         248
        .size:           8
        .value_kind:     hidden_global_offset_z
      - .offset:         256
        .size:           2
        .value_kind:     hidden_grid_dims
      - .offset:         312
        .size:           4
        .value_kind:     hidden_dynamic_lds_size
    .group_segment_fixed_size: 0
    .kernarg_segment_align: 8
    .kernarg_segment_size: 448
    .language:       OpenCL C
    .language_version:
      - 2
      - 0
    .max_flat_workgroup_size: 512
    .name:           _Z6mk_fwd4Args
    .private_segment_fixed_size: 0
    .sgpr_count:     108
    .sgpr_spill_count: 247
    .symbol:         _Z6mk_fwd4Args.kd
    .uniform_work_group_size: 1
    .uses_dynamic_stack: false
    .vgpr_count:     256
    .vgpr_spill_count: 0
    .wavefront_size: 64
